# LayerNorm row-loop loads (once-read rows) carry nt; on top of v61
# speedup vs baseline: 1.0057x; 1.0057x over previous
; __device__ __forceinline__ void ph_ln(const Args& a, int L, int which, bool final_, bool split, bool wr_x, bool res_inputs, int nblk, int b) {
;     ...
;     if (gw < M) ldrow(gw);
;     for (int r = gw; r < M; r += ngw) {
;         float v[4][8];
; #pragma unroll
;         for (int j = 0; j < 4; ++j)
; #pragma unroll
;             for (int e = 0; e < 4; ++e) { v[j][2 * e] = lo(zc[j][e]); v[j][2 * e + 1] = hi(zc[j][e]); }
;         if (!res_inputs) {
; #pragma unroll
;             for (int j = 0; j < 4; ++j)
; #pragma unroll
;                 for (int e = 0; e < 4; ++e) { v[j][2 * e] += ALPHA * lo(xc[j][e]); v[j][2 * e + 1] += ALPHA * hi(xc[j][e]); } }
;         if (r + ngw < M) ldrow(r + ngw);
;         if (split && r >= MP) {
; #pragma unroll
;             for (int p = 0; p < 3; ++p) { const u32x4* pr = (const u32x4*)(P + ((size_t)p * MS + (r - MP)) * D) + lane;
; #pragma unroll
;                 for (int j = 0; j < 4; ++j) { const u32x4 w = pr[64 * j];
; #pragma unroll
;                     for (int e = 0; e < 4; ++e) { v[j][2 * e] += lo(w[e]); v[j][2 * e + 1] += hi(w[e]); } } } }
;         if (res_inputs) { const f32x4* xr = (const f32x4*)(r < MP ? a.in[0] + (size_t)r * D : a.in[1] + (size_t)(r - MP) * D) + 2 * lane;
; #pragma unroll
;             for (int j = 0; j < 4; ++j)
; #pragma unroll
;                 for (int h = 0; h < 2; ++h) { const f32x4 x = xr[128 * j + h];
; #pragma unroll
;                     for (int e = 0; e < 4; ++e) v[j][4 * h + e] += ALPHA * x[e]; } }
;         float s = 0.f;
; #pragma unroll
;         for (int j = 0; j < 4; ++j) s += ((v[j][0] + v[j][1]) + (v[j][2] + v[j][3])) + ((v[j][4] + v[j][5]) + (v[j][6] + v[j][7]));
.LBB0_411:
	s_or_b64 exec, exec, s[4:5]
	v_add_u32_e32 v109, 0xffffe000, v106
	v_cmp_gt_i32_e32 vcc, s15, v106
	v_mov_b32_e32 v112, s9
	v_lshlrev_b32_e32 v142, 16, v94
	v_cndmask_b32_e32 v110, v109, v106, vcc
	v_mov_b32_e32 v109, s11
	v_cndmask_b32_e32 v111, 0, v107, vcc
	v_cndmask_b32_e32 v113, v109, v112, vcc
	v_mov_b32_e32 v109, s10
	v_mov_b32_e32 v112, s8
	v_cndmask_b32_e32 v112, v109, v112, vcc
	v_lshlrev_b64 v[110:111], 13, v[110:111]
	v_lshl_add_u64 v[110:111], v[112:113], 0, v[110:111]
	v_lshl_add_u64 v[138:139], v[110:111], 0, v[100:101]
	v_add_co_u32_e32 v134, vcc, s1, v138
	global_load_dwordx4 v[110:113], v[138:139], off offset:2048 nt
	global_load_dwordx4 v[114:117], v[138:139], off offset:2064 nt
	global_load_dwordx4 v[118:121], v[138:139], off nt
	global_load_dwordx4 v[122:125], v[138:139], off offset:16 nt
	v_addc_co_u32_e32 v135, vcc, 0, v139, vcc
	global_load_dwordx4 v[126:129], v[134:135], off nt
	v_lshl_add_u64 v[130:131], v[138:139], 0, s[20:21]
	global_load_dwordx4 v[130:133], v[130:131], off offset:16 nt
	s_nop 0
	global_load_dwordx4 v[134:137], v[134:135], off offset:2048 nt
	v_lshl_add_u64 v[138:139], v[138:139], 0, s[18:19]
	global_load_dwordx4 v[138:141], v[138:139], off offset:16 nt
	v_and_b32_e32 v143, 0xffff0000, v94
	v_lshlrev_b32_e32 v94, 16, v95
	v_and_b32_e32 v95, 0xffff0000, v95
	v_lshlrev_b32_e32 v144, 16, v96
	v_and_b32_e32 v145, 0xffff0000, v96
	v_lshlrev_b32_e32 v96, 16, v97
	v_and_b32_e32 v97, 0xffff0000, v97
	v_lshlrev_b32_e32 v146, 16, v90
	v_and_b32_e32 v147, 0xffff0000, v90
	v_lshlrev_b32_e32 v90, 16, v91
	v_and_b32_e32 v91, 0xffff0000, v91
	v_lshlrev_b32_e32 v148, 16, v92
	v_and_b32_e32 v149, 0xffff0000, v92
	v_lshlrev_b32_e32 v92, 16, v93
	v_and_b32_e32 v93, 0xffff0000, v93
	v_lshlrev_b32_e32 v150, 16, v86
	v_and_b32_e32 v151, 0xffff0000, v86
	v_lshlrev_b32_e32 v109, 16, v82
	v_and_b32_e32 v158, 0xffff0000, v82
	v_and_b32_e32 v155, 0xffff0000, v83
	v_lshlrev_b32_e32 v154, 16, v83
	v_and_b32_e32 v83, 0xffff0000, v84
	v_lshlrev_b32_e32 v82, 16, v84
	v_and_b32_e32 v157, 0xffff0000, v85
	v_lshlrev_b32_e32 v156, 16, v85
	v_lshlrev_b32_e32 v86, 16, v87
	v_and_b32_e32 v87, 0xffff0000, v87
	v_lshlrev_b32_e32 v152, 16, v88
	v_and_b32_e32 v153, 0xffff0000, v88
	v_lshlrev_b32_e32 v88, 16, v89
	v_and_b32_e32 v89, 0xffff0000, v89
	v_lshl_add_u64 v[106:107], v[106:107], 0, s[74:75]
	v_lshl_add_u64 v[102:103], v[102:103], 0, s[22:23]
	s_waitcnt vmcnt(7)
	v_pk_fma_f32 v[84:85], v[110:111], s[14:15], v[146:147] op_sel_hi:[1,0,1]
	v_pk_fma_f32 v[90:91], v[112:113], s[14:15], v[90:91] op_sel_hi:[1,0,1]
	s_waitcnt vmcnt(6)
	v_pk_fma_f32 v[110:111], v[114:115], s[14:15], v[148:149] op_sel_hi:[1,0,1]
	s_waitcnt vmcnt(4)
	v_pk_fma_f32 v[96:97], v[124:125], s[14:15], v[96:97] op_sel_hi:[1,0,1]
	v_pk_fma_f32 v[112:113], v[122:123], s[14:15], v[144:145] op_sel_hi:[1,0,1]
	v_pk_fma_f32 v[94:95], v[120:121], s[14:15], v[94:95] op_sel_hi:[1,0,1]
	v_pk_fma_f32 v[114:115], v[118:119], s[14:15], v[142:143] op_sel_hi:[1,0,1]
	v_pk_fma_f32 v[92:93], v[116:117], s[14:15], v[92:93] op_sel_hi:[1,0,1]
	s_waitcnt vmcnt(3)
	v_pk_fma_f32 v[116:117], v[126:127], s[14:15], v[150:151] op_sel_hi:[1,0,1]
	v_mov_b32_e32 v120, v94
	v_mov_b32_e32 v121, v96
	v_mov_b32_e32 v122, v95
	v_mov_b32_e32 v123, v97
	v_mov_b32_e32 v124, v114
	v_mov_b32_e32 v125, v112
	v_mov_b32_e32 v126, v115
	v_mov_b32_e32 v127, v113
	s_waitcnt vmcnt(1)
	v_mul_f32_e32 v142, 0x3fd744fd, v134
	v_pk_add_f32 v[120:121], v[120:121], v[122:123]
	v_pk_add_f32 v[122:123], v[124:125], v[126:127]
	v_pk_add_f32 v[124:125], v[84:85], v[84:85] op_sel:[0,1] op_sel_hi:[1,0]
	v_pk_add_f32 v[126:127], v[90:91], v[90:91] op_sel:[0,1] op_sel_hi:[1,0]
	v_pk_fma_f32 v[86:87], v[128:129], s[14:15], v[86:87] op_sel_hi:[1,0,1]
	v_mov_b32_e32 v125, v142
	v_mov_b32_e32 v127, v109
	v_pk_fma_f32 v[118:119], v[130:131], s[14:15], v[152:153] op_sel_hi:[1,0,1]
	v_pk_fma_f32 v[88:89], v[132:133], s[14:15], v[88:89] op_sel_hi:[1,0,1]
	v_mul_f32_e32 v143, 0x3fd744fd, v135
	v_pk_add_f32 v[130:131], v[116:117], v[116:117] op_sel:[0,1] op_sel_hi:[1,0]
	v_pk_add_f32 v[132:133], v[86:87], v[86:87] op_sel:[0,1] op_sel_hi:[1,0]
	v_pk_add_f32 v[120:121], v[122:123], v[120:121]
	s_waitcnt vmcnt(0)
	v_pk_fma_f32 v[82:83], v[138:139], s[14:15], v[82:83] op_sel_hi:[1,0,1]
	v_pk_fma_f32 v[122:123], v[136:137], s[14:15], v[154:155] op_sel_hi:[1,0,1]
	v_pk_add_f32 v[124:125], v[124:125], v[126:127]
	v_pk_add_f32 v[126:127], v[110:111], v[110:111] op_sel:[0,1] op_sel_hi:[1,0]
	v_pk_add_f32 v[136:137], v[92:93], v[92:93] op_sel:[0,1] op_sel_hi:[1,0]
	v_pk_fma_f32 v[128:129], v[140:141], s[14:15], v[156:157] op_sel_hi:[1,0,1]
	v_pk_add_f32 v[134:135], v[118:119], v[118:119] op_sel:[0,1] op_sel_hi:[1,0]
	v_pk_add_f32 v[140:141], v[88:89], v[88:89] op_sel:[0,1] op_sel_hi:[1,0]
	v_pk_add_f32 v[120:121], v[120:121], v[120:121] op_sel:[0,1] op_sel_hi:[1,0]
	v_mov_b32_e32 v127, v143
	v_mov_b32_e32 v137, v158
	v_mov_b32_e32 v131, v82
	v_mov_b32_e32 v133, v83
	v_pk_add_f32 v[126:127], v[126:127], v[136:137]
	v_mov_b32_e32 v135, v128
	v_mov_b32_e32 v141, v129
	v_pk_add_f32 v[130:131], v[130:131], v[132:133]
	v_mov_b32_e32 v121, v122
	v_mov_b32_e32 v132, v101
	v_mov_b32_e32 v133, v123
	v_pk_add_f32 v[136:137], v[124:125], v[126:127]
	v_pk_add_f32 v[134:135], v[134:135], v[140:141]
	v_pk_add_f32 v[120:121], v[120:121], v[132:133]
	v_pk_add_f32 v[130:131], v[130:131], v[134:135]
	v_pk_add_f32 v[120:121], v[136:137], v[120:121]
	v_mov_b32_e32 v126, v125
	v_pk_add_f32 v[120:121], v[120:121], v[130:131]
	s_nop 0
	v_add_f32_e32 v109, v120, v121
	s_nop 1
	v_add_f32_dpp v109, v109, v109 row_ror:1 row_mask:0xf bank_mask:0xf bound_ctrl:1
; __device__ __forceinline__ void ph_ln(const Args& a, int L, int which, bool final_, bool split, bool wr_x, bool res_inputs, int nblk, int b) {
;     ...
;         const float mean = wave_sum_dpp(s) * (1.f / D); float s2 = 0.f;
; #pragma unroll
;         for (int j = 0; j < 4; ++j)
; #pragma unroll
;             for (int e = 0; e < 8; ++e) { v[j][e] -= mean; s2 += v[j][e] * v[j][e]; }
;         const float rstd = 1.f / sqrtf(wave_sum_dpp(s2) * (1.f / D) + LN_EPS);
	s_nop 1
	v_add_f32_dpp v109, v109, v109 row_ror:2 row_mask:0xf bank_mask:0xf bound_ctrl:1
	s_nop 1
	v_add_f32_dpp v109, v109, v109 row_ror:4 row_mask:0xf bank_mask:0xf bound_ctrl:1
	s_nop 1
	v_add_f32_dpp v109, v109, v109 row_ror:8 row_mask:0xf bank_mask:0xf bound_ctrl:1
	s_nop 0
	v_readlane_b32 s6, v109, 16
	v_readlane_b32 s7, v109, 48
	v_readlane_b32 s4, v109, 0
	v_readlane_b32 s5, v109, 32
	v_mov_b32_e32 v120, s6
	v_mov_b32_e32 v121, s7
	v_pk_add_f32 v[120:121], s[4:5], v[120:121]
	s_nop 0
	v_add_f32_e32 v109, v120, v121
	v_mul_f32_e32 v120, 0x3a000000, v109
	v_pk_add_f32 v[114:115], v[114:115], v[120:121] op_sel_hi:[1,0] neg_lo:[0,1] neg_hi:[0,1]
	v_pk_add_f32 v[94:95], v[94:95], v[120:121] op_sel_hi:[1,0] neg_lo:[0,1] neg_hi:[0,1]
	v_pk_mul_f32 v[130:131], v[114:115], v[114:115]
	v_pk_mul_f32 v[132:133], v[94:95], v[94:95]
	v_add_f32_e32 v109, v130, v131
	v_pk_add_f32 v[112:113], v[112:113], v[120:121] op_sel_hi:[1,0] neg_lo:[0,1] neg_hi:[0,1]
	v_add_f32_e32 v109, v132, v109
	v_pk_mul_f32 v[134:135], v[112:113], v[112:113]
	v_add_f32_e32 v109, v133, v109
	v_pk_add_f32 v[96:97], v[96:97], v[120:121] op_sel_hi:[1,0] neg_lo:[0,1] neg_hi:[0,1]
	v_add_f32_e32 v109, v134, v109
	v_pk_mul_f32 v[136:137], v[96:97], v[96:97]
	v_add_f32_e32 v109, v135, v109
	v_pk_add_f32 v[150:151], v[84:85], v[120:121] op_sel_hi:[1,0] neg_lo:[0,1] neg_hi:[0,1]
	v_add_f32_e32 v109, v136, v109
	v_pk_mul_f32 v[84:85], v[150:151], v[150:151]
	v_add_f32_e32 v109, v137, v109
	v_pk_add_f32 v[90:91], v[90:91], v[120:121] op_sel_hi:[1,0] neg_lo:[0,1] neg_hi:[0,1]
	v_add_f32_e32 v84, v84, v109
	v_pk_mul_f32 v[148:149], v[90:91], v[90:91]
	v_add_f32_e32 v84, v85, v84
	v_pk_add_f32 v[110:111], v[110:111], v[120:121] op_sel_hi:[1,0] neg_lo:[0,1] neg_hi:[0,1]
	v_add_f32_e32 v84, v148, v84
	v_pk_mul_f32 v[146:147], v[110:111], v[110:111]
	v_add_f32_e32 v84, v149, v84
	v_pk_add_f32 v[92:93], v[92:93], v[120:121] op_sel_hi:[1,0] neg_lo:[0,1] neg_hi:[0,1]
	v_add_f32_e32 v84, v146, v84
	v_pk_mul_f32 v[144:145], v[92:93], v[92:93]
	v_add_f32_e32 v84, v147, v84
	v_pk_add_f32 v[116:117], v[116:117], v[120:121] op_sel_hi:[1,0] neg_lo:[0,1] neg_hi:[0,1]
	v_add_f32_e32 v84, v144, v84
	v_pk_mul_f32 v[158:159], v[116:117], v[116:117]
	v_add_f32_e32 v84, v145, v84
	v_pk_add_f32 v[86:87], v[86:87], v[120:121] op_sel_hi:[1,0] neg_lo:[0,1] neg_hi:[0,1]
	v_add_f32_e32 v84, v158, v84
	v_pk_mul_f32 v[156:157], v[86:87], v[86:87]
	v_add_f32_e32 v84, v159, v84
	v_pk_add_f32 v[118:119], v[118:119], v[120:121] op_sel_hi:[1,0] neg_lo:[0,1] neg_hi:[0,1]
	v_add_f32_e32 v84, v156, v84
	v_pk_mul_f32 v[154:155], v[118:119], v[118:119]
	v_add_f32_e32 v84, v157, v84
	v_pk_add_f32 v[88:89], v[88:89], v[120:121] op_sel_hi:[1,0] neg_lo:[0,1] neg_hi:[0,1]
	v_add_f32_e32 v84, v154, v84
	v_pk_mul_f32 v[152:153], v[88:89], v[88:89]
	v_add_f32_e32 v84, v155, v84
	v_pk_add_f32 v[122:123], v[122:123], v[120:121] op_sel_hi:[1,0] neg_lo:[0,1] neg_hi:[0,1]
	v_pk_add_f32 v[140:141], v[82:83], v[120:121] op_sel_hi:[1,0] neg_lo:[0,1] neg_hi:[0,1]
	v_pk_add_f32 v[128:129], v[128:129], v[120:121] op_sel_hi:[1,0] neg_lo:[0,1] neg_hi:[0,1]
	v_pk_add_f32 v[120:121], v[126:127], v[120:121] op_sel_hi:[1,0] neg_lo:[0,1] neg_hi:[0,1]
	v_add_f32_e32 v84, v152, v84
	v_pk_mul_f32 v[124:125], v[120:121], v[120:121]
	v_add_f32_e32 v84, v153, v84
	v_add_f32_e32 v84, v124, v84
	v_pk_mul_f32 v[138:139], v[122:123], v[122:123]
	v_add_f32_e32 v84, v125, v84
	v_add_f32_e32 v84, v138, v84
	v_pk_mul_f32 v[82:83], v[140:141], v[140:141]
	v_add_f32_e32 v84, v139, v84
	v_add_f32_e32 v82, v82, v84
	v_pk_mul_f32 v[142:143], v[128:129], v[128:129]
	v_add_f32_e32 v82, v83, v82
	v_add_f32_e32 v82, v142, v82
	v_add_f32_e32 v82, v143, v82
	v_lshl_add_u64 v[124:125], v[104:105], 0, v[98:99]
	v_lshl_add_u64 v[104:105], v[104:105], 0, s[22:23]
	v_add_f32_dpp v82, v82, v82 row_ror:1 row_mask:0xf bank_mask:0xf bound_ctrl:1
	s_nop 1
	v_add_f32_dpp v82, v82, v82 row_ror:2 row_mask:0xf bank_mask:0xf bound_ctrl:1
	s_nop 1
	v_add_f32_dpp v82, v82, v82 row_ror:4 row_mask:0xf bank_mask:0xf bound_ctrl:1
	s_nop 1
	v_add_f32_dpp v82, v82, v82 row_ror:8 row_mask:0xf bank_mask:0xf bound_ctrl:1
	s_nop 0
	v_readlane_b32 s6, v82, 16
	v_readlane_b32 s7, v82, 48
	v_readlane_b32 s4, v82, 0
	v_readlane_b32 s5, v82, 32
	v_mov_b32_e32 v82, s6
	v_mov_b32_e32 v83, s7
	v_pk_add_f32 v[82:83], s[4:5], v[82:83]
	s_nop 0
	v_add_f32_e32 v82, v82, v83
	v_fmamk_f32 v82, v82, 0x3a000000, v1
	v_mul_f32_e32 v83, 0x4f800000, v82
; __device__ __forceinline__ unsigned pk2(float lo, float hi) { const f32x2 v = {lo, hi}; return __builtin_bit_cast(unsigned, __builtin_convertvector(v, bf16x2_t)); }
; __device__ __forceinline__ void ph_ln(const Args& a, int L, int which, bool final_, bool split, bool wr_x, bool res_inputs, int nblk, int b) {
;     ...
;     auto ldrow = [&](int r) { const u32x4* zr = (const u32x4*)(Z + (size_t)r * D) + lane;
; #pragma unroll
;         for (int j = 0; j < 4; ++j) zc[j] = zr[64 * j];
;         if (!res_inputs) { const u32x4* xr = (const u32x4*)(XB + (size_t)r * D) + lane;
; #pragma unroll
;             for (int j = 0; j < 4; ++j) xc[j] = xr[64 * j]; } };
;     if (gw < M) ldrow(gw);
;     ...
;         const float rstd = 1.f / sqrtf(wave_sum_dpp(s2) * (1.f / D) + LN_EPS);
;         f32x4* xo = (f32x4*)(Xo + (size_t)r * D) + 2 * lane; u32x4* xb = (u32x4*)(XB + (size_t)r * D) + lane;
; #pragma unroll
;         for (int j = 0; j < 4; ++j) { f32x4 y[2];
; #pragma unroll
;             for (int h = 0; h < 2; ++h)
; #pragma unroll
;                 for (int e = 0; e < 4; ++e) y[h][e] = v[j][4 * h + e] * rstd * gg[j][h][e] + bb[j][h][e];
;             if (final_ || wr_x) { xo[128 * j] = y[0]; xo[128 * j + 1] = y[1]; }
;             if (!final_) { u32x4 w; w.x = pk2(y[0][0], y[0][1]); w.y = pk2(y[0][2], y[0][3]); w.z = pk2(y[1][0], y[1][1]); w.w = pk2(y[1][2], y[1][3]); xb[64 * j] = w; } }
	v_cmp_gt_f32_e32 vcc, s24, v82
	s_nop 1
	v_cndmask_b32_e32 v82, v82, v83, vcc
	v_sqrt_f32_e32 v83, v82
	s_nop 0
	v_add_u32_e32 v84, -1, v83
	v_fma_f32 v85, -v84, v83, v82
	v_cmp_ge_f32_e64 s[6:7], 0, v85
	v_add_u32_e32 v85, 1, v83
	s_nop 0
	v_cndmask_b32_e64 v84, v83, v84, s[6:7]
	v_fma_f32 v83, -v85, v83, v82
	v_cmp_lt_f32_e64 s[6:7], 0, v83
	s_nop 1
	v_cndmask_b32_e64 v83, v84, v85, s[6:7]
	v_mul_f32_e32 v84, 0x37800000, v83
	v_cndmask_b32_e32 v83, v83, v84, vcc
	v_cmp_class_f32_e32 vcc, v82, v108
	s_nop 1
	v_cndmask_b32_e32 v82, v83, v82, vcc
	v_div_scale_f32 v83, s[4:5], v82, v82, 1.0
	v_rcp_f32_e32 v84, v83
	s_nop 0
	v_fma_f32 v85, -v83, v84, 1.0
	v_fmac_f32_e32 v84, v85, v84
	v_div_scale_f32 v85, vcc, 1.0, v82, 1.0
	v_mul_f32_e32 v109, v85, v84
	v_fma_f32 v126, -v83, v109, v85
	v_fmac_f32_e32 v109, v126, v84
	v_fma_f32 v83, -v83, v109, v85
	v_div_fmas_f32 v83, v83, v84, v109
	v_div_fixup_f32 v126, v83, v82, 1.0
	v_pk_mul_f32 v[82:83], v[114:115], v[126:127] op_sel_hi:[1,0]
	v_pk_mul_f32 v[84:85], v[94:95], v[126:127] op_sel_hi:[1,0]
	v_pk_mul_f32 v[94:95], v[112:113], v[126:127] op_sel_hi:[1,0]
	v_pk_mul_f32 v[96:97], v[96:97], v[126:127] op_sel_hi:[1,0]
	v_pk_fma_f32 v[82:83], v[50:51], v[82:83], v[46:47]
	v_pk_fma_f32 v[84:85], v[52:53], v[84:85], v[48:49]
	v_pk_fma_f32 v[94:95], v[58:59], v[94:95], v[54:55]
	v_pk_fma_f32 v[96:97], v[60:61], v[96:97], v[56:57]
	v_cvt_pk_bf16_f32 v82, v82, v83
	v_cvt_pk_bf16_f32 v83, v84, v85
	v_cvt_pk_bf16_f32 v84, v94, v95
	v_cvt_pk_bf16_f32 v85, v96, v97
	global_store_dwordx4 v[124:125], v[82:85], off offset:-2048
	v_pk_mul_f32 v[92:93], v[92:93], v[126:127] op_sel_hi:[1,0]
	v_pk_mul_f32 v[88:89], v[88:89], v[126:127] op_sel_hi:[1,0]
	v_pk_mul_f32 v[82:83], v[150:151], v[126:127] op_sel_hi:[1,0]
	v_pk_mul_f32 v[84:85], v[90:91], v[126:127] op_sel_hi:[1,0]
	v_pk_mul_f32 v[90:91], v[110:111], v[126:127] op_sel_hi:[1,0]
	v_pk_fma_f32 v[82:83], v[34:35], v[82:83], v[30:31]
	v_pk_fma_f32 v[84:85], v[36:37], v[84:85], v[32:33]
	v_pk_fma_f32 v[90:91], v[42:43], v[90:91], v[38:39]
	v_pk_fma_f32 v[92:93], v[44:45], v[92:93], v[40:41]
	v_cvt_pk_bf16_f32 v82, v82, v83
	v_cvt_pk_bf16_f32 v83, v84, v85
	v_cvt_pk_bf16_f32 v84, v90, v91
	v_cvt_pk_bf16_f32 v85, v92, v93
	global_store_dwordx4 v[124:125], v[82:85], off offset:-1024
	v_pk_fma_f32 v[88:89], v[64:65], v[88:89], v[20:21]
	v_cmp_lt_i32_e32 vcc, s25, v106
	v_pk_mul_f32 v[82:83], v[116:117], v[126:127] op_sel_hi:[1,0]
	v_pk_mul_f32 v[84:85], v[86:87], v[126:127] op_sel_hi:[1,0]
	v_pk_mul_f32 v[86:87], v[118:119], v[126:127] op_sel_hi:[1,0]
	v_pk_fma_f32 v[82:83], v[26:27], v[82:83], v[14:15]
	v_pk_fma_f32 v[84:85], v[28:29], v[84:85], v[16:17]
	v_pk_fma_f32 v[86:87], v[62:63], v[86:87], v[18:19]
	v_cvt_pk_bf16_f32 v82, v82, v83
	v_cvt_pk_bf16_f32 v83, v84, v85
	v_cvt_pk_bf16_f32 v84, v86, v87
	v_cvt_pk_bf16_f32 v85, v88, v89
	global_store_dwordx4 v[124:125], v[82:85], off
	v_pk_mul_f32 v[86:87], v[140:141], v[126:127] op_sel_hi:[1,0]
	v_pk_mul_f32 v[88:89], v[128:129], v[126:127] op_sel_hi:[1,0]
	v_pk_mul_f32 v[82:83], v[120:121], v[126:127] op_sel_hi:[1,0]
	v_pk_mul_f32 v[84:85], v[122:123], v[126:127] op_sel_hi:[1,0]
	v_pk_fma_f32 v[82:83], v[6:7], v[82:83], v[2:3]
	v_pk_fma_f32 v[84:85], v[8:9], v[84:85], v[4:5]
	v_pk_fma_f32 v[86:87], v[22:23], v[86:87], v[10:11]
	v_pk_fma_f32 v[88:89], v[24:25], v[88:89], v[12:13]
	v_cvt_pk_bf16_f32 v82, v82, v83
	v_cvt_pk_bf16_f32 v83, v84, v85
	v_cvt_pk_bf16_f32 v84, v86, v87
	v_cvt_pk_bf16_f32 v85, v88, v89
	global_store_dwordx4 v[124:125], v[82:85], off offset:1024
	v_mov_b64_e32 v[88:89], v[72:73]
	v_mov_b64_e32 v[92:93], v[76:77]
	v_mov_b64_e32 v[84:85], v[68:69]
	v_mov_b64_e32 v[96:97], v[80:81]
	s_or_b64 s[12:13], vcc, s[12:13]
	v_mov_b64_e32 v[82:83], v[66:67]
	v_mov_b64_e32 v[86:87], v[70:71]
	v_mov_b64_e32 v[90:91], v[74:75]
	v_mov_b64_e32 v[94:95], v[78:79]
	s_andn2_b64 exec, exec, s[12:13]
	s_cbranch_execz .LBB0_414
.LBB0_412:
	v_add_u32_e32 v109, s74, v106
	v_cmp_gt_i32_e32 vcc, s0, v109
	s_and_saveexec_b64 s[4:5], vcc
	s_cbranch_execz .LBB0_411
	v_lshl_add_u64 v[66:67], v[102:103], 0, v[98:99]
	v_add_co_u32_e32 v110, vcc, 0x1e100000, v66
	s_nop 1
	v_addc_co_u32_e32 v111, vcc, 0, v67, vcc
	global_load_dwordx4 v[78:81], v[110:111], off nt
	global_load_dwordx4 v[74:77], v[110:111], off offset:1024 nt
	global_load_dwordx4 v[70:73], v[110:111], off offset:2048 nt
	global_load_dwordx4 v[66:69], v[110:111], off offset:3072 nt
	s_branch .LBB0_411

; __device__ __forceinline__ void ph_ln(const Args& a, int L, int which, bool final_, bool split, bool wr_x, bool res_inputs, int nblk, int b) {
;     ...
;     auto ldrow = [&](int r) { const u32x4* zr = (const u32x4*)(Z + (size_t)r * D) + lane;
; #pragma unroll
;         for (int j = 0; j < 4; ++j) zc[j] = zr[64 * j];
;         if (!res_inputs) { const u32x4* xr = (const u32x4*)(XB + (size_t)r * D) + lane;
; #pragma unroll
;             for (int j = 0; j < 4; ++j) xc[j] = xr[64 * j]; } };
;     if (gw < M) ldrow(gw);
;     for (int r = gw; r < M; r += ngw) {
;         float v[4][8];
; #pragma unroll
;         for (int j = 0; j < 4; ++j)
; #pragma unroll
;             for (int e = 0; e < 4; ++e) { v[j][2 * e] = lo(zc[j][e]); v[j][2 * e + 1] = hi(zc[j][e]); }
;         if (!res_inputs) {
; #pragma unroll
;             for (int j = 0; j < 4; ++j)
; #pragma unroll
;                 for (int e = 0; e < 4; ++e) { v[j][2 * e] += ALPHA * lo(xc[j][e]); v[j][2 * e + 1] += ALPHA * hi(xc[j][e]); } }
.LBB0_601:
	v_add_u32_e32 v158, s74, v156
	v_cmp_gt_i32_e32 vcc, s1, v158
	v_cmp_lt_i32_e64 s[6:7], s15, v158
	s_and_saveexec_b64 s[4:5], vcc
	s_cbranch_execz .LBB0_603
	v_lshl_add_u64 v[82:83], v[136:137], 0, v[132:133]
	v_add_co_u32_e32 v66, vcc, 0x1e100000, v82
	s_nop 1
	v_addc_co_u32_e32 v67, vcc, 0, v83, vcc
	v_add_co_u32_e32 v82, vcc, 0x1b900000, v82
	global_load_dwordx4 v[78:81], v[66:67], off nt
	global_load_dwordx4 v[74:77], v[66:67], off offset:1024 nt
	global_load_dwordx4 v[70:73], v[66:67], off offset:2048 nt
	s_nop 0
	global_load_dwordx4 v[66:69], v[66:67], off offset:3072 nt
	v_addc_co_u32_e32 v83, vcc, 0, v83, vcc
	global_load_dwordx4 v[94:97], v[82:83], off nt
	global_load_dwordx4 v[90:93], v[82:83], off offset:1024 nt
	global_load_dwordx4 v[86:89], v[82:83], off offset:2048 nt
	s_nop 0
	global_load_dwordx4 v[82:85], v[82:83], off offset:3072 nt
.LBB0_603:
	s_or_b64 exec, exec, s[4:5]
	v_and_b32_e32 v140, 0xffff0000, v122
	v_lshlrev_b32_e32 v141, 16, v122
	v_and_b32_e32 v142, 0xffff0000, v126
	v_lshlrev_b32_e32 v143, 16, v126
	v_and_b32_e32 v122, 0xffff0000, v123
	v_lshlrev_b32_e32 v123, 16, v123
	v_and_b32_e32 v126, 0xffff0000, v127
	v_lshlrev_b32_e32 v127, 16, v127
	v_pk_fma_f32 v[140:141], v[142:143], s[14:15], v[140:141] op_sel_hi:[1,0,1]
	v_pk_fma_f32 v[122:123], v[126:127], s[14:15], v[122:123] op_sel_hi:[1,0,1]
	v_and_b32_e32 v126, 0xffff0000, v124
	v_lshlrev_b32_e32 v127, 16, v124
	v_and_b32_e32 v142, 0xffff0000, v128
	v_lshlrev_b32_e32 v143, 16, v128
	v_and_b32_e32 v124, 0xffff0000, v125
	v_lshlrev_b32_e32 v125, 16, v125
	v_and_b32_e32 v128, 0xffff0000, v129
	v_lshlrev_b32_e32 v129, 16, v129
	v_pk_fma_f32 v[126:127], v[142:143], s[14:15], v[126:127] op_sel_hi:[1,0,1]
	v_pk_fma_f32 v[128:129], v[128:129], s[14:15], v[124:125] op_sel_hi:[1,0,1]
	v_and_b32_e32 v124, 0xffff0000, v114
	v_lshlrev_b32_e32 v125, 16, v114
	v_and_b32_e32 v142, 0xffff0000, v118
	v_lshlrev_b32_e32 v143, 16, v118
	v_and_b32_e32 v114, 0xffff0000, v115
	v_lshlrev_b32_e32 v115, 16, v115
	v_and_b32_e32 v118, 0xffff0000, v119
	v_lshlrev_b32_e32 v119, 16, v119
	v_pk_fma_f32 v[124:125], v[142:143], s[14:15], v[124:125] op_sel_hi:[1,0,1]
	v_pk_fma_f32 v[142:143], v[118:119], s[14:15], v[114:115] op_sel_hi:[1,0,1]
	v_and_b32_e32 v114, 0xffff0000, v116
	v_lshlrev_b32_e32 v115, 16, v116
	v_and_b32_e32 v118, 0xffff0000, v120
	v_lshlrev_b32_e32 v119, 16, v120
	v_pk_fma_f32 v[144:145], v[118:119], s[14:15], v[114:115] op_sel_hi:[1,0,1]
	v_and_b32_e32 v114, 0xffff0000, v117
	v_lshlrev_b32_e32 v115, 16, v117
	v_and_b32_e32 v116, 0xffff0000, v121
	v_lshlrev_b32_e32 v117, 16, v121
	v_pk_fma_f32 v[116:117], v[116:117], s[14:15], v[114:115] op_sel_hi:[1,0,1]
	v_and_b32_e32 v114, 0xffff0000, v106
	v_lshlrev_b32_e32 v115, 16, v106
	v_and_b32_e32 v118, 0xffff0000, v110
	v_lshlrev_b32_e32 v119, 16, v110
	v_and_b32_e32 v106, 0xffff0000, v107
	v_lshlrev_b32_e32 v107, 16, v107
	v_and_b32_e32 v110, 0xffff0000, v111
	v_lshlrev_b32_e32 v111, 16, v111
	v_pk_fma_f32 v[114:115], v[118:119], s[14:15], v[114:115] op_sel_hi:[1,0,1]
	v_pk_fma_f32 v[118:119], v[110:111], s[14:15], v[106:107] op_sel_hi:[1,0,1]
	v_and_b32_e32 v106, 0xffff0000, v108
	v_lshlrev_b32_e32 v107, 16, v108
	v_and_b32_e32 v110, 0xffff0000, v112
	v_lshlrev_b32_e32 v111, 16, v112
	v_pk_fma_f32 v[120:121], v[110:111], s[14:15], v[106:107] op_sel_hi:[1,0,1]
	v_and_b32_e32 v106, 0xffff0000, v109
	v_lshlrev_b32_e32 v107, 16, v109
	v_and_b32_e32 v108, 0xffff0000, v113
	v_lshlrev_b32_e32 v109, 16, v113
	v_pk_fma_f32 v[146:147], v[108:109], s[14:15], v[106:107] op_sel_hi:[1,0,1]
	v_and_b32_e32 v106, 0xffff0000, v98
	v_lshlrev_b32_e32 v107, 16, v98
	v_and_b32_e32 v108, 0xffff0000, v102
	v_lshlrev_b32_e32 v109, 16, v102
	v_and_b32_e32 v98, 0xffff0000, v99
	v_lshlrev_b32_e32 v99, 16, v99
	v_and_b32_e32 v102, 0xffff0000, v103
	v_lshlrev_b32_e32 v103, 16, v103
	v_pk_fma_f32 v[150:151], v[102:103], s[14:15], v[98:99] op_sel_hi:[1,0,1]
	v_and_b32_e32 v98, 0xffff0000, v100
	v_lshlrev_b32_e32 v99, 16, v100
	v_and_b32_e32 v102, 0xffff0000, v104
	v_lshlrev_b32_e32 v103, 16, v104
	v_pk_fma_f32 v[152:153], v[102:103], s[14:15], v[98:99] op_sel_hi:[1,0,1]
	v_and_b32_e32 v98, 0xffff0000, v101
	v_lshlrev_b32_e32 v99, 16, v101
	v_and_b32_e32 v100, 0xffff0000, v105
	v_lshlrev_b32_e32 v101, 16, v105
	v_pk_fma_f32 v[148:149], v[108:109], s[14:15], v[106:107] op_sel_hi:[1,0,1]
	v_pk_fma_f32 v[154:155], v[100:101], s[14:15], v[98:99] op_sel_hi:[1,0,1]
	v_cmp_lt_i32_e32 vcc, s16, v156
	s_and_saveexec_b64 s[8:9], vcc
	s_cbranch_execz .LBB0_600
; __device__ __forceinline__ void ph_ln(const Args& a, int L, int which, bool final_, bool split, bool wr_x, bool res_inputs, int nblk, int b) {
;     ...
;         if (split && r >= MP) {
; #pragma unroll
;             for (int p = 0; p < 3; ++p) { const u32x4* pr = (const u32x4*)(P + ((size_t)p * MS + (r - MP)) * D) + lane;
; #pragma unroll
;                 for (int j = 0; j < 4; ++j) { const u32x4 w = pr[64 * j];
; #pragma unroll
;                     for (int e = 0; e < 4; ++e) { v[j][2 * e] += lo(w[e]); v[j][2 * e + 1] += hi(w[e]); } } } }
	v_add_u32_e32 v130, 0xffffe000, v156
	v_lshlrev_b64 v[98:99], 12, v[130:131]
	v_lshl_add_u64 v[98:99], v[134:135], 0, v[98:99]
	v_add_co_u32_e32 v100, vcc, s17, v98
	global_load_dwordx4 v[160:163], v[98:99], off nt
	global_load_dwordx4 v[106:109], v[98:99], off offset:1024 nt
	v_addc_co_u32_e32 v101, vcc, 0, v99, vcc
	global_load_dwordx4 v[164:167], v[100:101], off nt
	global_load_dwordx4 v[110:113], v[100:101], off offset:1024 nt
	v_add_co_u32_e32 v188, vcc, s18, v98
	s_waitcnt vmcnt(3)
	v_and_b32_e32 v192, 0xffff0000, v160
	v_addc_co_u32_e32 v189, vcc, 0, v99, vcc
	global_load_dwordx4 v[168:171], v[188:189], off nt
	global_load_dwordx4 v[172:175], v[188:189], off offset:1024 nt
	global_load_dwordx4 v[176:179], v[98:99], off offset:2048 nt
	global_load_dwordx4 v[180:183], v[100:101], off offset:2048 nt
	global_load_dwordx4 v[102:105], v[98:99], off offset:3072 nt
	s_nop 0
	global_load_dwordx4 v[98:101], v[100:101], off offset:3072 nt
	s_nop 0
	global_load_dwordx4 v[184:187], v[188:189], off offset:2048 nt
	s_nop 0
	global_load_dwordx4 v[188:191], v[188:189], off offset:3072 nt
	v_lshlrev_b32_e32 v193, 16, v160
	v_and_b32_e32 v160, 0xffff0000, v161
	v_lshlrev_b32_e32 v161, 16, v161
	v_and_b32_e32 v194, 0xffff0000, v162
	v_lshlrev_b32_e32 v195, 16, v162
	v_and_b32_e32 v162, 0xffff0000, v163
	v_lshlrev_b32_e32 v163, 16, v163
	s_waitcnt vmcnt(10)
	v_and_b32_e32 v196, 0xffff0000, v106
	v_lshlrev_b32_e32 v197, 16, v106
	v_and_b32_e32 v106, 0xffff0000, v107
	v_lshlrev_b32_e32 v107, 16, v107
	v_and_b32_e32 v198, 0xffff0000, v108
	v_lshlrev_b32_e32 v199, 16, v108
	v_pk_add_f32 v[122:123], v[122:123], v[160:161]
	v_pk_add_f32 v[128:129], v[128:129], v[162:163]
	v_pk_add_f32 v[106:107], v[142:143], v[106:107]
	v_pk_add_f32 v[142:143], v[144:145], v[198:199]
	s_waitcnt vmcnt(9)
	v_and_b32_e32 v144, 0xffff0000, v164
	v_lshlrev_b32_e32 v145, 16, v164
	v_and_b32_e32 v160, 0xffff0000, v165
	v_lshlrev_b32_e32 v161, 16, v165
	v_and_b32_e32 v162, 0xffff0000, v166
	v_lshlrev_b32_e32 v163, 16, v166
	v_and_b32_e32 v164, 0xffff0000, v167
	v_lshlrev_b32_e32 v165, 16, v167
	s_waitcnt vmcnt(8)
	v_and_b32_e32 v166, 0xffff0000, v110
	v_lshlrev_b32_e32 v167, 16, v110
	v_and_b32_e32 v110, 0xffff0000, v111
	v_lshlrev_b32_e32 v111, 16, v111
	v_pk_add_f32 v[140:141], v[140:141], v[192:193]
	v_and_b32_e32 v192, 0xffff0000, v112
	v_lshlrev_b32_e32 v193, 16, v112
	v_pk_add_f32 v[106:107], v[106:107], v[110:111]
	v_pk_add_f32 v[140:141], v[140:141], v[144:145]
	v_pk_add_f32 v[122:123], v[122:123], v[160:161]
	v_and_b32_e32 v108, 0xffff0000, v113
	v_pk_add_f32 v[126:127], v[126:127], v[194:195]
	v_pk_add_f32 v[124:125], v[124:125], v[196:197]
	v_pk_add_f32 v[126:127], v[126:127], v[162:163]
	v_pk_add_f32 v[128:129], v[128:129], v[164:165]
	v_pk_add_f32 v[124:125], v[124:125], v[166:167]
	s_waitcnt vmcnt(7)
	v_and_b32_e32 v144, 0xffff0000, v168
	s_waitcnt vmcnt(6)
	v_and_b32_e32 v110, 0xffff0000, v173
	v_lshlrev_b32_e32 v111, 16, v173
	v_lshlrev_b32_e32 v145, 16, v168
	v_and_b32_e32 v160, 0xffff0000, v169
	v_lshlrev_b32_e32 v161, 16, v169
	v_pk_add_f32 v[168:169], v[142:143], v[192:193]
	v_pk_add_f32 v[142:143], v[106:107], v[110:111]
	v_and_b32_e32 v106, 0xffff0000, v109
	v_lshlrev_b32_e32 v107, 16, v109
	v_pk_add_f32 v[106:107], v[116:117], v[106:107]
	v_lshlrev_b32_e32 v109, 16, v113
	v_pk_add_f32 v[106:107], v[106:107], v[108:109]
	v_and_b32_e32 v108, 0xffff0000, v175
	v_lshlrev_b32_e32 v109, 16, v175
	v_pk_add_f32 v[116:117], v[106:107], v[108:109]
	s_waitcnt vmcnt(5)
	v_and_b32_e32 v106, 0xffff0000, v176
	v_lshlrev_b32_e32 v107, 16, v176
	v_pk_add_f32 v[106:107], v[114:115], v[106:107]
	s_waitcnt vmcnt(4)
	v_and_b32_e32 v108, 0xffff0000, v180
	v_lshlrev_b32_e32 v109, 16, v180
	v_pk_add_f32 v[106:107], v[106:107], v[108:109]
	s_waitcnt vmcnt(1)
	v_and_b32_e32 v108, 0xffff0000, v184
	v_lshlrev_b32_e32 v109, 16, v184
	v_pk_add_f32 v[114:115], v[106:107], v[108:109]
	v_and_b32_e32 v106, 0xffff0000, v177
	v_lshlrev_b32_e32 v107, 16, v177
	v_pk_add_f32 v[106:107], v[118:119], v[106:107]
	v_and_b32_e32 v108, 0xffff0000, v181
	v_lshlrev_b32_e32 v109, 16, v181
	v_pk_add_f32 v[106:107], v[106:107], v[108:109]
	v_and_b32_e32 v108, 0xffff0000, v185
	v_lshlrev_b32_e32 v109, 16, v185
	v_pk_add_f32 v[118:119], v[106:107], v[108:109]
	v_and_b32_e32 v106, 0xffff0000, v178
	v_lshlrev_b32_e32 v107, 16, v178
	v_pk_add_f32 v[106:107], v[120:121], v[106:107]
	v_and_b32_e32 v108, 0xffff0000, v182
	v_lshlrev_b32_e32 v109, 16, v182
	v_pk_add_f32 v[106:107], v[106:107], v[108:109]
	v_and_b32_e32 v108, 0xffff0000, v186
	v_lshlrev_b32_e32 v109, 16, v186
	v_pk_add_f32 v[120:121], v[106:107], v[108:109]
	v_and_b32_e32 v106, 0xffff0000, v179
	v_lshlrev_b32_e32 v107, 16, v179
	v_pk_add_f32 v[106:107], v[146:147], v[106:107]
	v_and_b32_e32 v108, 0xffff0000, v183
	v_lshlrev_b32_e32 v109, 16, v183
	v_pk_add_f32 v[106:107], v[106:107], v[108:109]
	v_and_b32_e32 v108, 0xffff0000, v187
	v_lshlrev_b32_e32 v109, 16, v187
	v_pk_add_f32 v[146:147], v[106:107], v[108:109]
	v_and_b32_e32 v106, 0xffff0000, v102
	v_lshlrev_b32_e32 v107, 16, v102
	v_and_b32_e32 v102, 0xffff0000, v103
	v_lshlrev_b32_e32 v103, 16, v103
	v_and_b32_e32 v108, 0xffff0000, v98
	v_lshlrev_b32_e32 v109, 16, v98
	v_pk_add_f32 v[102:103], v[150:151], v[102:103]
	v_and_b32_e32 v98, 0xffff0000, v99
	v_lshlrev_b32_e32 v99, 16, v99
	v_pk_add_f32 v[98:99], v[102:103], v[98:99]
	s_waitcnt vmcnt(0)
	v_and_b32_e32 v102, 0xffff0000, v189
	v_lshlrev_b32_e32 v103, 16, v189
	v_pk_add_f32 v[150:151], v[98:99], v[102:103]
	v_and_b32_e32 v98, 0xffff0000, v104
	v_lshlrev_b32_e32 v99, 16, v104
	v_pk_add_f32 v[98:99], v[152:153], v[98:99]
	v_and_b32_e32 v102, 0xffff0000, v100
	v_lshlrev_b32_e32 v103, 16, v100
	v_pk_add_f32 v[98:99], v[98:99], v[102:103]
	v_and_b32_e32 v102, 0xffff0000, v190
	v_lshlrev_b32_e32 v103, 16, v190
	v_pk_add_f32 v[152:153], v[98:99], v[102:103]
	v_and_b32_e32 v98, 0xffff0000, v105
	v_lshlrev_b32_e32 v99, 16, v105
	v_pk_add_f32 v[106:107], v[148:149], v[106:107]
	v_pk_add_f32 v[98:99], v[154:155], v[98:99]
	v_and_b32_e32 v100, 0xffff0000, v101
	v_lshlrev_b32_e32 v101, 16, v101
	v_and_b32_e32 v162, 0xffff0000, v170
	v_lshlrev_b32_e32 v163, 16, v170
	v_and_b32_e32 v164, 0xffff0000, v171
	v_lshlrev_b32_e32 v165, 16, v171
	v_and_b32_e32 v166, 0xffff0000, v172
	v_lshlrev_b32_e32 v167, 16, v172
	v_and_b32_e32 v170, 0xffff0000, v174
	v_lshlrev_b32_e32 v171, 16, v174
	v_pk_add_f32 v[106:107], v[106:107], v[108:109]
	v_and_b32_e32 v108, 0xffff0000, v188
	v_lshlrev_b32_e32 v109, 16, v188
	v_pk_add_f32 v[98:99], v[98:99], v[100:101]
	v_and_b32_e32 v100, 0xffff0000, v191
	v_lshlrev_b32_e32 v101, 16, v191
	v_pk_add_f32 v[140:141], v[140:141], v[144:145]
	v_pk_add_f32 v[122:123], v[122:123], v[160:161]
	v_pk_add_f32 v[126:127], v[126:127], v[162:163]
	v_pk_add_f32 v[128:129], v[128:129], v[164:165]
	v_pk_add_f32 v[124:125], v[124:125], v[166:167]
	v_pk_add_f32 v[144:145], v[168:169], v[170:171]
	v_pk_add_f32 v[148:149], v[106:107], v[108:109]
	v_pk_add_f32 v[154:155], v[98:99], v[100:101]
	s_branch .LBB0_600

; __device__ __forceinline__ void ph_ln(const Args& a, int L, int which, bool final_, bool split, bool wr_x, bool res_inputs, int nblk, int b) {
;     ...
;     auto ldrow = [&](int r) { const u32x4* zr = (const u32x4*)(Z + (size_t)r * D) + lane;
; #pragma unroll
;         for (int j = 0; j < 4; ++j) zc[j] = zr[64 * j];
;         if (!res_inputs) { const u32x4* xr = (const u32x4*)(XB + (size_t)r * D) + lane;
; #pragma unroll
;             for (int j = 0; j < 4; ++j) xc[j] = xr[64 * j]; } };
;     if (gw < M) ldrow(gw);
;     for (int r = gw; r < M; r += ngw) {
;         float v[4][8];
; #pragma unroll
;         for (int j = 0; j < 4; ++j)
; #pragma unroll
;             for (int e = 0; e < 4; ++e) { v[j][2 * e] = lo(zc[j][e]); v[j][2 * e + 1] = hi(zc[j][e]); }
;         if (!res_inputs) {
; #pragma unroll
;             for (int j = 0; j < 4; ++j)
; #pragma unroll
;                 for (int e = 0; e < 4; ++e) { v[j][2 * e] += ALPHA * lo(xc[j][e]); v[j][2 * e + 1] += ALPHA * hi(xc[j][e]); } }
.LBB0_1099:
	v_add_u32_e32 v159, s74, v156
	v_cmp_gt_i32_e32 vcc, s17, v159
	v_cmp_lt_i32_e64 s[6:7], s18, v159
	s_and_saveexec_b64 s[4:5], vcc
	s_cbranch_execz .LBB0_1101
	v_lshl_add_u64 v[82:83], v[136:137], 0, v[132:133]
	v_add_co_u32_e32 v66, vcc, 0x1e100000, v82
	s_nop 1
	v_addc_co_u32_e32 v67, vcc, 0, v83, vcc
	v_add_co_u32_e32 v82, vcc, 0x1b900000, v82
	global_load_dwordx4 v[78:81], v[66:67], off nt
	global_load_dwordx4 v[74:77], v[66:67], off offset:1024 nt
	global_load_dwordx4 v[70:73], v[66:67], off offset:2048 nt
	s_nop 0
	global_load_dwordx4 v[66:69], v[66:67], off offset:3072 nt
	v_addc_co_u32_e32 v83, vcc, 0, v83, vcc
	global_load_dwordx4 v[94:97], v[82:83], off nt
	global_load_dwordx4 v[90:93], v[82:83], off offset:1024 nt
	global_load_dwordx4 v[86:89], v[82:83], off offset:2048 nt
	s_nop 0
	global_load_dwordx4 v[82:85], v[82:83], off offset:3072 nt
.LBB0_1101:
	s_or_b64 exec, exec, s[4:5]
	v_and_b32_e32 v140, 0xffff0000, v122
	v_lshlrev_b32_e32 v141, 16, v122
	v_and_b32_e32 v142, 0xffff0000, v126
	v_lshlrev_b32_e32 v143, 16, v126
	v_and_b32_e32 v122, 0xffff0000, v123
	v_lshlrev_b32_e32 v123, 16, v123
	v_and_b32_e32 v126, 0xffff0000, v127
	v_lshlrev_b32_e32 v127, 16, v127
	v_pk_fma_f32 v[140:141], v[142:143], s[16:17], v[140:141] op_sel_hi:[1,0,1]
	v_pk_fma_f32 v[122:123], v[126:127], s[16:17], v[122:123] op_sel_hi:[1,0,1]
	v_and_b32_e32 v126, 0xffff0000, v124
	v_lshlrev_b32_e32 v127, 16, v124
	v_and_b32_e32 v142, 0xffff0000, v128
	v_lshlrev_b32_e32 v143, 16, v128
	v_and_b32_e32 v124, 0xffff0000, v125
	v_lshlrev_b32_e32 v125, 16, v125
	v_and_b32_e32 v128, 0xffff0000, v129
	v_lshlrev_b32_e32 v129, 16, v129
	v_pk_fma_f32 v[126:127], v[142:143], s[16:17], v[126:127] op_sel_hi:[1,0,1]
	v_pk_fma_f32 v[128:129], v[128:129], s[16:17], v[124:125] op_sel_hi:[1,0,1]
	v_and_b32_e32 v124, 0xffff0000, v114
	v_lshlrev_b32_e32 v125, 16, v114
	v_and_b32_e32 v142, 0xffff0000, v118
	v_lshlrev_b32_e32 v143, 16, v118
	v_and_b32_e32 v114, 0xffff0000, v115
	v_lshlrev_b32_e32 v115, 16, v115
	v_and_b32_e32 v118, 0xffff0000, v119
	v_lshlrev_b32_e32 v119, 16, v119
	v_pk_fma_f32 v[124:125], v[142:143], s[16:17], v[124:125] op_sel_hi:[1,0,1]
	v_pk_fma_f32 v[142:143], v[118:119], s[16:17], v[114:115] op_sel_hi:[1,0,1]
	v_and_b32_e32 v114, 0xffff0000, v116
	v_lshlrev_b32_e32 v115, 16, v116
	v_and_b32_e32 v118, 0xffff0000, v120
	v_lshlrev_b32_e32 v119, 16, v120
	v_pk_fma_f32 v[144:145], v[118:119], s[16:17], v[114:115] op_sel_hi:[1,0,1]
	v_and_b32_e32 v114, 0xffff0000, v117
	v_lshlrev_b32_e32 v115, 16, v117
	v_and_b32_e32 v116, 0xffff0000, v121
	v_lshlrev_b32_e32 v117, 16, v121
	v_pk_fma_f32 v[116:117], v[116:117], s[16:17], v[114:115] op_sel_hi:[1,0,1]
	v_and_b32_e32 v114, 0xffff0000, v106
	v_lshlrev_b32_e32 v115, 16, v106
	v_and_b32_e32 v118, 0xffff0000, v110
	v_lshlrev_b32_e32 v119, 16, v110
	v_and_b32_e32 v106, 0xffff0000, v107
	v_lshlrev_b32_e32 v107, 16, v107
	v_and_b32_e32 v110, 0xffff0000, v111
	v_lshlrev_b32_e32 v111, 16, v111
	v_pk_fma_f32 v[114:115], v[118:119], s[16:17], v[114:115] op_sel_hi:[1,0,1]
	v_pk_fma_f32 v[118:119], v[110:111], s[16:17], v[106:107] op_sel_hi:[1,0,1]
	v_and_b32_e32 v106, 0xffff0000, v108
	v_lshlrev_b32_e32 v107, 16, v108
	v_and_b32_e32 v110, 0xffff0000, v112
	v_lshlrev_b32_e32 v111, 16, v112
	v_pk_fma_f32 v[120:121], v[110:111], s[16:17], v[106:107] op_sel_hi:[1,0,1]
	v_and_b32_e32 v106, 0xffff0000, v109
	v_lshlrev_b32_e32 v107, 16, v109
	v_and_b32_e32 v108, 0xffff0000, v113
	v_lshlrev_b32_e32 v109, 16, v113
	v_pk_fma_f32 v[146:147], v[108:109], s[16:17], v[106:107] op_sel_hi:[1,0,1]
	v_and_b32_e32 v106, 0xffff0000, v98
	v_lshlrev_b32_e32 v107, 16, v98
	v_and_b32_e32 v108, 0xffff0000, v102
	v_lshlrev_b32_e32 v109, 16, v102
	v_and_b32_e32 v98, 0xffff0000, v99
	v_lshlrev_b32_e32 v99, 16, v99
	v_and_b32_e32 v102, 0xffff0000, v103
	v_lshlrev_b32_e32 v103, 16, v103
	v_pk_fma_f32 v[150:151], v[102:103], s[16:17], v[98:99] op_sel_hi:[1,0,1]
	v_and_b32_e32 v98, 0xffff0000, v100
	v_lshlrev_b32_e32 v99, 16, v100
	v_and_b32_e32 v102, 0xffff0000, v104
	v_lshlrev_b32_e32 v103, 16, v104
	v_pk_fma_f32 v[152:153], v[102:103], s[16:17], v[98:99] op_sel_hi:[1,0,1]
	v_and_b32_e32 v98, 0xffff0000, v101
	v_lshlrev_b32_e32 v99, 16, v101
	v_and_b32_e32 v100, 0xffff0000, v105
	v_lshlrev_b32_e32 v101, 16, v105
	v_pk_fma_f32 v[148:149], v[108:109], s[16:17], v[106:107] op_sel_hi:[1,0,1]
	v_pk_fma_f32 v[154:155], v[100:101], s[16:17], v[98:99] op_sel_hi:[1,0,1]
	v_cmp_lt_i32_e32 vcc, s19, v156
	s_and_saveexec_b64 s[8:9], vcc
	s_cbranch_execz .LBB0_1098
; __device__ __forceinline__ void ph_ln(const Args& a, int L, int which, bool final_, bool split, bool wr_x, bool res_inputs, int nblk, int b) {
;     ...
;         if (split && r >= MP) {
; #pragma unroll
;             for (int p = 0; p < 3; ++p) { const u32x4* pr = (const u32x4*)(P + ((size_t)p * MS + (r - MP)) * D) + lane;
; #pragma unroll
;                 for (int j = 0; j < 4; ++j) { const u32x4 w = pr[64 * j];
; #pragma unroll
;                     for (int e = 0; e < 4; ++e) { v[j][2 * e] += lo(w[e]); v[j][2 * e + 1] += hi(w[e]); } } } }
	v_add_u32_e32 v130, 0xffffe000, v156
	v_lshlrev_b64 v[98:99], 12, v[130:131]
	v_lshl_add_u64 v[98:99], v[134:135], 0, v[98:99]
	v_add_co_u32_e32 v100, vcc, s20, v98
	global_load_dwordx4 v[160:163], v[98:99], off nt
	global_load_dwordx4 v[106:109], v[98:99], off offset:1024 nt
	v_addc_co_u32_e32 v101, vcc, 0, v99, vcc
	global_load_dwordx4 v[164:167], v[100:101], off nt
	global_load_dwordx4 v[110:113], v[100:101], off offset:1024 nt
	v_add_co_u32_e32 v188, vcc, s21, v98
	s_waitcnt vmcnt(3)
	v_and_b32_e32 v192, 0xffff0000, v160
	v_addc_co_u32_e32 v189, vcc, 0, v99, vcc
	global_load_dwordx4 v[168:171], v[188:189], off nt
	global_load_dwordx4 v[172:175], v[188:189], off offset:1024 nt
	global_load_dwordx4 v[176:179], v[98:99], off offset:2048 nt
	global_load_dwordx4 v[180:183], v[100:101], off offset:2048 nt
	global_load_dwordx4 v[102:105], v[98:99], off offset:3072 nt
	s_nop 0
	global_load_dwordx4 v[98:101], v[100:101], off offset:3072 nt
	s_nop 0
	global_load_dwordx4 v[184:187], v[188:189], off offset:2048 nt
	s_nop 0
	global_load_dwordx4 v[188:191], v[188:189], off offset:3072 nt
	v_lshlrev_b32_e32 v193, 16, v160
	v_and_b32_e32 v160, 0xffff0000, v161
	v_lshlrev_b32_e32 v161, 16, v161
	v_and_b32_e32 v194, 0xffff0000, v162
	v_lshlrev_b32_e32 v195, 16, v162
	v_and_b32_e32 v162, 0xffff0000, v163
	v_lshlrev_b32_e32 v163, 16, v163
	s_waitcnt vmcnt(10)
	v_and_b32_e32 v196, 0xffff0000, v106
	v_lshlrev_b32_e32 v197, 16, v106
	v_and_b32_e32 v106, 0xffff0000, v107
	v_lshlrev_b32_e32 v107, 16, v107
	v_and_b32_e32 v198, 0xffff0000, v108
	v_lshlrev_b32_e32 v199, 16, v108
	v_pk_add_f32 v[122:123], v[122:123], v[160:161]
	v_pk_add_f32 v[128:129], v[128:129], v[162:163]
	v_pk_add_f32 v[106:107], v[142:143], v[106:107]
	v_pk_add_f32 v[142:143], v[144:145], v[198:199]
	s_waitcnt vmcnt(9)
	v_and_b32_e32 v144, 0xffff0000, v164
	v_lshlrev_b32_e32 v145, 16, v164
	v_and_b32_e32 v160, 0xffff0000, v165
	v_lshlrev_b32_e32 v161, 16, v165
	v_and_b32_e32 v162, 0xffff0000, v166
	v_lshlrev_b32_e32 v163, 16, v166
	v_and_b32_e32 v164, 0xffff0000, v167
	v_lshlrev_b32_e32 v165, 16, v167
	s_waitcnt vmcnt(8)
	v_and_b32_e32 v166, 0xffff0000, v110
	v_lshlrev_b32_e32 v167, 16, v110
	v_and_b32_e32 v110, 0xffff0000, v111
	v_lshlrev_b32_e32 v111, 16, v111
	v_pk_add_f32 v[140:141], v[140:141], v[192:193]
	v_and_b32_e32 v192, 0xffff0000, v112
	v_lshlrev_b32_e32 v193, 16, v112
	v_pk_add_f32 v[106:107], v[106:107], v[110:111]
	v_pk_add_f32 v[140:141], v[140:141], v[144:145]
	v_pk_add_f32 v[122:123], v[122:123], v[160:161]
	v_and_b32_e32 v108, 0xffff0000, v113
	v_pk_add_f32 v[126:127], v[126:127], v[194:195]
	v_pk_add_f32 v[124:125], v[124:125], v[196:197]
	v_pk_add_f32 v[126:127], v[126:127], v[162:163]
	v_pk_add_f32 v[128:129], v[128:129], v[164:165]
	v_pk_add_f32 v[124:125], v[124:125], v[166:167]
	s_waitcnt vmcnt(7)
	v_and_b32_e32 v144, 0xffff0000, v168
	s_waitcnt vmcnt(6)
	v_and_b32_e32 v110, 0xffff0000, v173
	v_lshlrev_b32_e32 v111, 16, v173
	v_lshlrev_b32_e32 v145, 16, v168
	v_and_b32_e32 v160, 0xffff0000, v169
	v_lshlrev_b32_e32 v161, 16, v169
	v_pk_add_f32 v[168:169], v[142:143], v[192:193]
	v_pk_add_f32 v[142:143], v[106:107], v[110:111]
	v_and_b32_e32 v106, 0xffff0000, v109
	v_lshlrev_b32_e32 v107, 16, v109
	v_pk_add_f32 v[106:107], v[116:117], v[106:107]
	v_lshlrev_b32_e32 v109, 16, v113
	v_pk_add_f32 v[106:107], v[106:107], v[108:109]
	v_and_b32_e32 v108, 0xffff0000, v175
	v_lshlrev_b32_e32 v109, 16, v175
	v_pk_add_f32 v[116:117], v[106:107], v[108:109]
	s_waitcnt vmcnt(5)
	v_and_b32_e32 v106, 0xffff0000, v176
	v_lshlrev_b32_e32 v107, 16, v176
	v_pk_add_f32 v[106:107], v[114:115], v[106:107]
	s_waitcnt vmcnt(4)
	v_and_b32_e32 v108, 0xffff0000, v180
	v_lshlrev_b32_e32 v109, 16, v180
	v_pk_add_f32 v[106:107], v[106:107], v[108:109]
	s_waitcnt vmcnt(1)
	v_and_b32_e32 v108, 0xffff0000, v184
	v_lshlrev_b32_e32 v109, 16, v184
	v_pk_add_f32 v[114:115], v[106:107], v[108:109]
	v_and_b32_e32 v106, 0xffff0000, v177
	v_lshlrev_b32_e32 v107, 16, v177
	v_pk_add_f32 v[106:107], v[118:119], v[106:107]
	v_and_b32_e32 v108, 0xffff0000, v181
	v_lshlrev_b32_e32 v109, 16, v181
	v_pk_add_f32 v[106:107], v[106:107], v[108:109]
	v_and_b32_e32 v108, 0xffff0000, v185
	v_lshlrev_b32_e32 v109, 16, v185
	v_pk_add_f32 v[118:119], v[106:107], v[108:109]
	v_and_b32_e32 v106, 0xffff0000, v178
	v_lshlrev_b32_e32 v107, 16, v178
	v_pk_add_f32 v[106:107], v[120:121], v[106:107]
	v_and_b32_e32 v108, 0xffff0000, v182
	v_lshlrev_b32_e32 v109, 16, v182
	v_pk_add_f32 v[106:107], v[106:107], v[108:109]
	v_and_b32_e32 v108, 0xffff0000, v186
	v_lshlrev_b32_e32 v109, 16, v186
	v_pk_add_f32 v[120:121], v[106:107], v[108:109]
	v_and_b32_e32 v106, 0xffff0000, v179
	v_lshlrev_b32_e32 v107, 16, v179
	v_pk_add_f32 v[106:107], v[146:147], v[106:107]
	v_and_b32_e32 v108, 0xffff0000, v183
	v_lshlrev_b32_e32 v109, 16, v183
	v_pk_add_f32 v[106:107], v[106:107], v[108:109]
	v_and_b32_e32 v108, 0xffff0000, v187
	v_lshlrev_b32_e32 v109, 16, v187
	v_pk_add_f32 v[146:147], v[106:107], v[108:109]
	v_and_b32_e32 v106, 0xffff0000, v102
	v_lshlrev_b32_e32 v107, 16, v102
	v_and_b32_e32 v102, 0xffff0000, v103
	v_lshlrev_b32_e32 v103, 16, v103
	v_and_b32_e32 v108, 0xffff0000, v98
	v_lshlrev_b32_e32 v109, 16, v98
	v_pk_add_f32 v[102:103], v[150:151], v[102:103]
	v_and_b32_e32 v98, 0xffff0000, v99
	v_lshlrev_b32_e32 v99, 16, v99
	v_pk_add_f32 v[98:99], v[102:103], v[98:99]
	s_waitcnt vmcnt(0)
	v_and_b32_e32 v102, 0xffff0000, v189
	v_lshlrev_b32_e32 v103, 16, v189
	v_pk_add_f32 v[150:151], v[98:99], v[102:103]
	v_and_b32_e32 v98, 0xffff0000, v104
	v_lshlrev_b32_e32 v99, 16, v104
	v_pk_add_f32 v[98:99], v[152:153], v[98:99]
	v_and_b32_e32 v102, 0xffff0000, v100
	v_lshlrev_b32_e32 v103, 16, v100
	v_pk_add_f32 v[98:99], v[98:99], v[102:103]
	v_and_b32_e32 v102, 0xffff0000, v190
	v_lshlrev_b32_e32 v103, 16, v190
	v_pk_add_f32 v[152:153], v[98:99], v[102:103]
	v_and_b32_e32 v98, 0xffff0000, v105
	v_lshlrev_b32_e32 v99, 16, v105
	v_pk_add_f32 v[106:107], v[148:149], v[106:107]
	v_pk_add_f32 v[98:99], v[154:155], v[98:99]
	v_and_b32_e32 v100, 0xffff0000, v101
	v_lshlrev_b32_e32 v101, 16, v101
	v_and_b32_e32 v162, 0xffff0000, v170
	v_lshlrev_b32_e32 v163, 16, v170
	v_and_b32_e32 v164, 0xffff0000, v171
	v_lshlrev_b32_e32 v165, 16, v171
	v_and_b32_e32 v166, 0xffff0000, v172
	v_lshlrev_b32_e32 v167, 16, v172
	v_and_b32_e32 v170, 0xffff0000, v174
	v_lshlrev_b32_e32 v171, 16, v174
	v_pk_add_f32 v[106:107], v[106:107], v[108:109]
	v_and_b32_e32 v108, 0xffff0000, v188
	v_lshlrev_b32_e32 v109, 16, v188
	v_pk_add_f32 v[98:99], v[98:99], v[100:101]
	v_and_b32_e32 v100, 0xffff0000, v191
	v_lshlrev_b32_e32 v101, 16, v191
	v_pk_add_f32 v[140:141], v[140:141], v[144:145]
	v_pk_add_f32 v[122:123], v[122:123], v[160:161]
	v_pk_add_f32 v[126:127], v[126:127], v[162:163]
	v_pk_add_f32 v[128:129], v[128:129], v[164:165]
	v_pk_add_f32 v[124:125], v[124:125], v[166:167]
	v_pk_add_f32 v[144:145], v[168:169], v[170:171]
	v_pk_add_f32 v[148:149], v[106:107], v[108:109]
	v_pk_add_f32 v[154:155], v[98:99], v[100:101]
	s_branch .LBB0_1098

; __device__ __forceinline__ void ph_ln(const Args& a, int L, int which, bool final_, bool split, bool wr_x, bool res_inputs, int nblk, int b) {
;     ...
;     auto ldrow = [&](int r) { const u32x4* zr = (const u32x4*)(Z + (size_t)r * D) + lane;
; #pragma unroll
;         for (int j = 0; j < 4; ++j) zc[j] = zr[64 * j];
;         if (!res_inputs) { const u32x4* xr = (const u32x4*)(XB + (size_t)r * D) + lane;
; #pragma unroll
;             for (int j = 0; j < 4; ++j) xc[j] = xr[64 * j]; } };
;     if (gw < M) ldrow(gw);
;     for (int r = gw; r < M; r += ngw) {
;         float v[4][8];
; #pragma unroll
;         for (int j = 0; j < 4; ++j)
; #pragma unroll
;             for (int e = 0; e < 4; ++e) { v[j][2 * e] = lo(zc[j][e]); v[j][2 * e + 1] = hi(zc[j][e]); }
;         if (!res_inputs) {
; #pragma unroll
;             for (int j = 0; j < 4; ++j)
; #pragma unroll
;                 for (int e = 0; e < 4; ++e) { v[j][2 * e] += ALPHA * lo(xc[j][e]); v[j][2 * e + 1] += ALPHA * hi(xc[j][e]); } }
.LBB0_1290:
	v_add_u32_e32 v159, s74, v156
	v_cmp_gt_i32_e32 vcc, s1, v159
	v_cmp_lt_i32_e64 s[8:9], s15, v159
	s_and_saveexec_b64 s[4:5], vcc
	s_cbranch_execz .LBB0_1292
	v_lshl_add_u64 v[82:83], v[136:137], 0, v[132:133]
	v_add_co_u32_e32 v66, vcc, 0x1e100000, v82
	s_nop 1
	v_addc_co_u32_e32 v67, vcc, 0, v83, vcc
	v_add_co_u32_e32 v82, vcc, 0x1b900000, v82
	global_load_dwordx4 v[78:81], v[66:67], off nt
	global_load_dwordx4 v[74:77], v[66:67], off offset:1024 nt
	global_load_dwordx4 v[70:73], v[66:67], off offset:2048 nt
	s_nop 0
	global_load_dwordx4 v[66:69], v[66:67], off offset:3072 nt
	v_addc_co_u32_e32 v83, vcc, 0, v83, vcc
	global_load_dwordx4 v[94:97], v[82:83], off nt
	global_load_dwordx4 v[90:93], v[82:83], off offset:1024 nt
	global_load_dwordx4 v[86:89], v[82:83], off offset:2048 nt
	s_nop 0
	global_load_dwordx4 v[82:85], v[82:83], off offset:3072 nt
.LBB0_1292:
	s_or_b64 exec, exec, s[4:5]
	v_and_b32_e32 v140, 0xffff0000, v122
	v_lshlrev_b32_e32 v141, 16, v122
	v_and_b32_e32 v142, 0xffff0000, v126
	v_lshlrev_b32_e32 v143, 16, v126
	v_and_b32_e32 v122, 0xffff0000, v123
	v_lshlrev_b32_e32 v123, 16, v123
	v_and_b32_e32 v126, 0xffff0000, v127
	v_lshlrev_b32_e32 v127, 16, v127
	v_pk_fma_f32 v[140:141], v[142:143], s[14:15], v[140:141] op_sel_hi:[1,0,1]
	v_pk_fma_f32 v[122:123], v[126:127], s[14:15], v[122:123] op_sel_hi:[1,0,1]
	v_and_b32_e32 v126, 0xffff0000, v124
	v_lshlrev_b32_e32 v127, 16, v124
	v_and_b32_e32 v142, 0xffff0000, v128
	v_lshlrev_b32_e32 v143, 16, v128
	v_and_b32_e32 v124, 0xffff0000, v125
	v_lshlrev_b32_e32 v125, 16, v125
	v_and_b32_e32 v128, 0xffff0000, v129
	v_lshlrev_b32_e32 v129, 16, v129
	v_pk_fma_f32 v[126:127], v[142:143], s[14:15], v[126:127] op_sel_hi:[1,0,1]
	v_pk_fma_f32 v[128:129], v[128:129], s[14:15], v[124:125] op_sel_hi:[1,0,1]
	v_and_b32_e32 v124, 0xffff0000, v114
	v_lshlrev_b32_e32 v125, 16, v114
	v_and_b32_e32 v142, 0xffff0000, v118
	v_lshlrev_b32_e32 v143, 16, v118
	v_and_b32_e32 v114, 0xffff0000, v115
	v_lshlrev_b32_e32 v115, 16, v115
	v_and_b32_e32 v118, 0xffff0000, v119
	v_lshlrev_b32_e32 v119, 16, v119
	v_pk_fma_f32 v[124:125], v[142:143], s[14:15], v[124:125] op_sel_hi:[1,0,1]
	v_pk_fma_f32 v[142:143], v[118:119], s[14:15], v[114:115] op_sel_hi:[1,0,1]
	v_and_b32_e32 v114, 0xffff0000, v116
	v_lshlrev_b32_e32 v115, 16, v116
	v_and_b32_e32 v118, 0xffff0000, v120
	v_lshlrev_b32_e32 v119, 16, v120
	v_pk_fma_f32 v[144:145], v[118:119], s[14:15], v[114:115] op_sel_hi:[1,0,1]
	v_and_b32_e32 v114, 0xffff0000, v117
	v_lshlrev_b32_e32 v115, 16, v117
	v_and_b32_e32 v116, 0xffff0000, v121
	v_lshlrev_b32_e32 v117, 16, v121
	v_pk_fma_f32 v[116:117], v[116:117], s[14:15], v[114:115] op_sel_hi:[1,0,1]
	v_and_b32_e32 v114, 0xffff0000, v106
	v_lshlrev_b32_e32 v115, 16, v106
	v_and_b32_e32 v118, 0xffff0000, v110
	v_lshlrev_b32_e32 v119, 16, v110
	v_and_b32_e32 v106, 0xffff0000, v107
	v_lshlrev_b32_e32 v107, 16, v107
	v_and_b32_e32 v110, 0xffff0000, v111
	v_lshlrev_b32_e32 v111, 16, v111
	v_pk_fma_f32 v[114:115], v[118:119], s[14:15], v[114:115] op_sel_hi:[1,0,1]
	v_pk_fma_f32 v[118:119], v[110:111], s[14:15], v[106:107] op_sel_hi:[1,0,1]
	v_and_b32_e32 v106, 0xffff0000, v108
	v_lshlrev_b32_e32 v107, 16, v108
	v_and_b32_e32 v110, 0xffff0000, v112
	v_lshlrev_b32_e32 v111, 16, v112
	v_pk_fma_f32 v[120:121], v[110:111], s[14:15], v[106:107] op_sel_hi:[1,0,1]
	v_and_b32_e32 v106, 0xffff0000, v109
	v_lshlrev_b32_e32 v107, 16, v109
	v_and_b32_e32 v108, 0xffff0000, v113
	v_lshlrev_b32_e32 v109, 16, v113
	v_pk_fma_f32 v[146:147], v[108:109], s[14:15], v[106:107] op_sel_hi:[1,0,1]
	v_and_b32_e32 v106, 0xffff0000, v98
	v_lshlrev_b32_e32 v107, 16, v98
	v_and_b32_e32 v108, 0xffff0000, v102
	v_lshlrev_b32_e32 v109, 16, v102
	v_and_b32_e32 v98, 0xffff0000, v99
	v_lshlrev_b32_e32 v99, 16, v99
	v_and_b32_e32 v102, 0xffff0000, v103
	v_lshlrev_b32_e32 v103, 16, v103
	v_pk_fma_f32 v[150:151], v[102:103], s[14:15], v[98:99] op_sel_hi:[1,0,1]
	v_and_b32_e32 v98, 0xffff0000, v100
	v_lshlrev_b32_e32 v99, 16, v100
	v_and_b32_e32 v102, 0xffff0000, v104
	v_lshlrev_b32_e32 v103, 16, v104
	v_pk_fma_f32 v[152:153], v[102:103], s[14:15], v[98:99] op_sel_hi:[1,0,1]
	v_and_b32_e32 v98, 0xffff0000, v101
	v_lshlrev_b32_e32 v99, 16, v101
	v_and_b32_e32 v100, 0xffff0000, v105
	v_lshlrev_b32_e32 v101, 16, v105
	v_pk_fma_f32 v[148:149], v[108:109], s[14:15], v[106:107] op_sel_hi:[1,0,1]
	v_pk_fma_f32 v[154:155], v[100:101], s[14:15], v[98:99] op_sel_hi:[1,0,1]
	v_cmp_lt_i32_e32 vcc, s16, v156
	s_and_saveexec_b64 s[10:11], vcc
	s_cbranch_execz .LBB0_1289
; __device__ __forceinline__ void ph_ln(const Args& a, int L, int which, bool final_, bool split, bool wr_x, bool res_inputs, int nblk, int b) {
;     ...
;         if (split && r >= MP) {
; #pragma unroll
;             for (int p = 0; p < 3; ++p) { const u32x4* pr = (const u32x4*)(P + ((size_t)p * MS + (r - MP)) * D) + lane;
; #pragma unroll
;                 for (int j = 0; j < 4; ++j) { const u32x4 w = pr[64 * j];
; #pragma unroll
;                     for (int e = 0; e < 4; ++e) { v[j][2 * e] += lo(w[e]); v[j][2 * e + 1] += hi(w[e]); } } } }
	v_add_u32_e32 v130, 0xffffe000, v156
	v_lshlrev_b64 v[98:99], 12, v[130:131]
	v_lshl_add_u64 v[98:99], v[134:135], 0, v[98:99]
	v_add_co_u32_e32 v100, vcc, s17, v98
	global_load_dwordx4 v[160:163], v[98:99], off nt
	global_load_dwordx4 v[106:109], v[98:99], off offset:1024 nt
	v_addc_co_u32_e32 v101, vcc, 0, v99, vcc
	global_load_dwordx4 v[164:167], v[100:101], off nt
	global_load_dwordx4 v[110:113], v[100:101], off offset:1024 nt
	v_add_co_u32_e32 v188, vcc, s18, v98
	s_waitcnt vmcnt(3)
	v_and_b32_e32 v192, 0xffff0000, v160
	v_addc_co_u32_e32 v189, vcc, 0, v99, vcc
	global_load_dwordx4 v[168:171], v[188:189], off nt
	global_load_dwordx4 v[172:175], v[188:189], off offset:1024 nt
	global_load_dwordx4 v[176:179], v[98:99], off offset:2048 nt
	global_load_dwordx4 v[180:183], v[100:101], off offset:2048 nt
	global_load_dwordx4 v[102:105], v[98:99], off offset:3072 nt
	s_nop 0
	global_load_dwordx4 v[98:101], v[100:101], off offset:3072 nt
	s_nop 0
	global_load_dwordx4 v[184:187], v[188:189], off offset:2048 nt
	s_nop 0
	global_load_dwordx4 v[188:191], v[188:189], off offset:3072 nt
	v_lshlrev_b32_e32 v193, 16, v160
	v_and_b32_e32 v160, 0xffff0000, v161
	v_lshlrev_b32_e32 v161, 16, v161
	v_and_b32_e32 v194, 0xffff0000, v162
	v_lshlrev_b32_e32 v195, 16, v162
	v_and_b32_e32 v162, 0xffff0000, v163
	v_lshlrev_b32_e32 v163, 16, v163
	s_waitcnt vmcnt(10)
	v_and_b32_e32 v196, 0xffff0000, v106
	v_lshlrev_b32_e32 v197, 16, v106
	v_and_b32_e32 v106, 0xffff0000, v107
	v_lshlrev_b32_e32 v107, 16, v107
	v_and_b32_e32 v198, 0xffff0000, v108
	v_lshlrev_b32_e32 v199, 16, v108
	v_pk_add_f32 v[122:123], v[122:123], v[160:161]
	v_pk_add_f32 v[128:129], v[128:129], v[162:163]
	v_pk_add_f32 v[106:107], v[142:143], v[106:107]
	v_pk_add_f32 v[142:143], v[144:145], v[198:199]
	s_waitcnt vmcnt(9)
	v_and_b32_e32 v144, 0xffff0000, v164
	v_lshlrev_b32_e32 v145, 16, v164
	v_and_b32_e32 v160, 0xffff0000, v165
	v_lshlrev_b32_e32 v161, 16, v165
	v_and_b32_e32 v162, 0xffff0000, v166
	v_lshlrev_b32_e32 v163, 16, v166
	v_and_b32_e32 v164, 0xffff0000, v167
	v_lshlrev_b32_e32 v165, 16, v167
	s_waitcnt vmcnt(8)
	v_and_b32_e32 v166, 0xffff0000, v110
	v_lshlrev_b32_e32 v167, 16, v110
	v_and_b32_e32 v110, 0xffff0000, v111
	v_lshlrev_b32_e32 v111, 16, v111
	v_pk_add_f32 v[140:141], v[140:141], v[192:193]
	v_and_b32_e32 v192, 0xffff0000, v112
	v_lshlrev_b32_e32 v193, 16, v112
	v_pk_add_f32 v[106:107], v[106:107], v[110:111]
	v_pk_add_f32 v[140:141], v[140:141], v[144:145]
	v_pk_add_f32 v[122:123], v[122:123], v[160:161]
	v_and_b32_e32 v108, 0xffff0000, v113
	v_pk_add_f32 v[126:127], v[126:127], v[194:195]
	v_pk_add_f32 v[124:125], v[124:125], v[196:197]
	v_pk_add_f32 v[126:127], v[126:127], v[162:163]
	v_pk_add_f32 v[128:129], v[128:129], v[164:165]
	v_pk_add_f32 v[124:125], v[124:125], v[166:167]
	s_waitcnt vmcnt(7)
	v_and_b32_e32 v144, 0xffff0000, v168
	s_waitcnt vmcnt(6)
	v_and_b32_e32 v110, 0xffff0000, v173
	v_lshlrev_b32_e32 v111, 16, v173
	v_lshlrev_b32_e32 v145, 16, v168
	v_and_b32_e32 v160, 0xffff0000, v169
	v_lshlrev_b32_e32 v161, 16, v169
	v_pk_add_f32 v[168:169], v[142:143], v[192:193]
	v_pk_add_f32 v[142:143], v[106:107], v[110:111]
	v_and_b32_e32 v106, 0xffff0000, v109
	v_lshlrev_b32_e32 v107, 16, v109
	v_pk_add_f32 v[106:107], v[116:117], v[106:107]
	v_lshlrev_b32_e32 v109, 16, v113
	v_pk_add_f32 v[106:107], v[106:107], v[108:109]
	v_and_b32_e32 v108, 0xffff0000, v175
	v_lshlrev_b32_e32 v109, 16, v175
	v_pk_add_f32 v[116:117], v[106:107], v[108:109]
	s_waitcnt vmcnt(5)
	v_and_b32_e32 v106, 0xffff0000, v176
	v_lshlrev_b32_e32 v107, 16, v176
	v_pk_add_f32 v[106:107], v[114:115], v[106:107]
	s_waitcnt vmcnt(4)
	v_and_b32_e32 v108, 0xffff0000, v180
	v_lshlrev_b32_e32 v109, 16, v180
	v_pk_add_f32 v[106:107], v[106:107], v[108:109]
	s_waitcnt vmcnt(1)
	v_and_b32_e32 v108, 0xffff0000, v184
	v_lshlrev_b32_e32 v109, 16, v184
	v_pk_add_f32 v[114:115], v[106:107], v[108:109]
	v_and_b32_e32 v106, 0xffff0000, v177
	v_lshlrev_b32_e32 v107, 16, v177
	v_pk_add_f32 v[106:107], v[118:119], v[106:107]
	v_and_b32_e32 v108, 0xffff0000, v181
	v_lshlrev_b32_e32 v109, 16, v181
	v_pk_add_f32 v[106:107], v[106:107], v[108:109]
	v_and_b32_e32 v108, 0xffff0000, v185
	v_lshlrev_b32_e32 v109, 16, v185
	v_pk_add_f32 v[118:119], v[106:107], v[108:109]
	v_and_b32_e32 v106, 0xffff0000, v178
	v_lshlrev_b32_e32 v107, 16, v178
	v_pk_add_f32 v[106:107], v[120:121], v[106:107]
	v_and_b32_e32 v108, 0xffff0000, v182
	v_lshlrev_b32_e32 v109, 16, v182
	v_pk_add_f32 v[106:107], v[106:107], v[108:109]
	v_and_b32_e32 v108, 0xffff0000, v186
	v_lshlrev_b32_e32 v109, 16, v186
	v_pk_add_f32 v[120:121], v[106:107], v[108:109]
	v_and_b32_e32 v106, 0xffff0000, v179
	v_lshlrev_b32_e32 v107, 16, v179
	v_pk_add_f32 v[106:107], v[146:147], v[106:107]
	v_and_b32_e32 v108, 0xffff0000, v183
	v_lshlrev_b32_e32 v109, 16, v183
	v_pk_add_f32 v[106:107], v[106:107], v[108:109]
	v_and_b32_e32 v108, 0xffff0000, v187
	v_lshlrev_b32_e32 v109, 16, v187
	v_pk_add_f32 v[146:147], v[106:107], v[108:109]
	v_and_b32_e32 v106, 0xffff0000, v102
	v_lshlrev_b32_e32 v107, 16, v102
	v_and_b32_e32 v102, 0xffff0000, v103
	v_lshlrev_b32_e32 v103, 16, v103
	v_and_b32_e32 v108, 0xffff0000, v98
	v_lshlrev_b32_e32 v109, 16, v98
	v_pk_add_f32 v[102:103], v[150:151], v[102:103]
	v_and_b32_e32 v98, 0xffff0000, v99
	v_lshlrev_b32_e32 v99, 16, v99
	v_pk_add_f32 v[98:99], v[102:103], v[98:99]
	s_waitcnt vmcnt(0)
	v_and_b32_e32 v102, 0xffff0000, v189
	v_lshlrev_b32_e32 v103, 16, v189
	v_pk_add_f32 v[150:151], v[98:99], v[102:103]
	v_and_b32_e32 v98, 0xffff0000, v104
	v_lshlrev_b32_e32 v99, 16, v104
	v_pk_add_f32 v[98:99], v[152:153], v[98:99]
	v_and_b32_e32 v102, 0xffff0000, v100
	v_lshlrev_b32_e32 v103, 16, v100
	v_pk_add_f32 v[98:99], v[98:99], v[102:103]
	v_and_b32_e32 v102, 0xffff0000, v190
	v_lshlrev_b32_e32 v103, 16, v190
	v_pk_add_f32 v[152:153], v[98:99], v[102:103]
	v_and_b32_e32 v98, 0xffff0000, v105
	v_lshlrev_b32_e32 v99, 16, v105
	v_pk_add_f32 v[106:107], v[148:149], v[106:107]
	v_pk_add_f32 v[98:99], v[154:155], v[98:99]
	v_and_b32_e32 v100, 0xffff0000, v101
	v_lshlrev_b32_e32 v101, 16, v101
	v_and_b32_e32 v162, 0xffff0000, v170
	v_lshlrev_b32_e32 v163, 16, v170
	v_and_b32_e32 v164, 0xffff0000, v171
	v_lshlrev_b32_e32 v165, 16, v171
	v_and_b32_e32 v166, 0xffff0000, v172
	v_lshlrev_b32_e32 v167, 16, v172
	v_and_b32_e32 v170, 0xffff0000, v174
	v_lshlrev_b32_e32 v171, 16, v174
	v_pk_add_f32 v[106:107], v[106:107], v[108:109]
	v_and_b32_e32 v108, 0xffff0000, v188
	v_lshlrev_b32_e32 v109, 16, v188
	v_pk_add_f32 v[98:99], v[98:99], v[100:101]
	v_and_b32_e32 v100, 0xffff0000, v191
	v_lshlrev_b32_e32 v101, 16, v191
	v_pk_add_f32 v[140:141], v[140:141], v[144:145]
	v_pk_add_f32 v[122:123], v[122:123], v[160:161]
	v_pk_add_f32 v[126:127], v[126:127], v[162:163]
	v_pk_add_f32 v[128:129], v[128:129], v[164:165]
	v_pk_add_f32 v[124:125], v[124:125], v[166:167]
	v_pk_add_f32 v[144:145], v[168:169], v[170:171]
	v_pk_add_f32 v[148:149], v[106:107], v[108:109]
	v_pk_add_f32 v[154:155], v[98:99], v[100:101]
	s_branch .LBB0_1289

; __device__ __forceinline__ void ph_ln(const Args& a, int L, int which, bool final_, bool split, bool wr_x, bool res_inputs, int nblk, int b) {
;     ...
;     auto ldrow = [&](int r) { const u32x4* zr = (const u32x4*)(Z + (size_t)r * D) + lane;
; #pragma unroll
;         for (int j = 0; j < 4; ++j) zc[j] = zr[64 * j];
;         if (!res_inputs) { const u32x4* xr = (const u32x4*)(XB + (size_t)r * D) + lane;
; #pragma unroll
;             for (int j = 0; j < 4; ++j) xc[j] = xr[64 * j]; } };
;     if (gw < M) ldrow(gw);
;     for (int r = gw; r < M; r += ngw) {
;         float v[4][8];
; #pragma unroll
;         for (int j = 0; j < 4; ++j)
; #pragma unroll
;             for (int e = 0; e < 4; ++e) { v[j][2 * e] = lo(zc[j][e]); v[j][2 * e + 1] = hi(zc[j][e]); }
;         if (!res_inputs) {
; #pragma unroll
;             for (int j = 0; j < 4; ++j)
; #pragma unroll
;                 for (int e = 0; e < 4; ++e) { v[j][2 * e] += ALPHA * lo(xc[j][e]); v[j][2 * e + 1] += ALPHA * hi(xc[j][e]); } }
.LBB0_1777:
	v_add_u32_e32 v158, s74, v156
	v_cmp_gt_i32_e32 vcc, s1, v158
	v_cmp_lt_i32_e64 s[8:9], s17, v158
	s_and_saveexec_b64 s[4:5], vcc
	s_cbranch_execz .LBB0_1779
	v_lshl_add_u64 v[82:83], v[136:137], 0, v[132:133]
	v_add_co_u32_e32 v66, vcc, 0x1e100000, v82
	s_nop 1
	v_addc_co_u32_e32 v67, vcc, 0, v83, vcc
	v_add_co_u32_e32 v82, vcc, 0x1b900000, v82
	global_load_dwordx4 v[78:81], v[66:67], off nt
	global_load_dwordx4 v[74:77], v[66:67], off offset:1024 nt
	global_load_dwordx4 v[70:73], v[66:67], off offset:2048 nt
	s_nop 0
	global_load_dwordx4 v[66:69], v[66:67], off offset:3072 nt
	v_addc_co_u32_e32 v83, vcc, 0, v83, vcc
	global_load_dwordx4 v[94:97], v[82:83], off nt
	global_load_dwordx4 v[90:93], v[82:83], off offset:1024 nt
	global_load_dwordx4 v[86:89], v[82:83], off offset:2048 nt
	s_nop 0
	global_load_dwordx4 v[82:85], v[82:83], off offset:3072 nt
.LBB0_1779:
	s_or_b64 exec, exec, s[4:5]
	v_and_b32_e32 v140, 0xffff0000, v122
	v_lshlrev_b32_e32 v141, 16, v122
	v_and_b32_e32 v142, 0xffff0000, v126
	v_lshlrev_b32_e32 v143, 16, v126
	v_and_b32_e32 v122, 0xffff0000, v123
	v_lshlrev_b32_e32 v123, 16, v123
	v_and_b32_e32 v126, 0xffff0000, v127
	v_lshlrev_b32_e32 v127, 16, v127
	v_pk_fma_f32 v[140:141], v[142:143], s[16:17], v[140:141] op_sel_hi:[1,0,1]
	v_pk_fma_f32 v[122:123], v[126:127], s[16:17], v[122:123] op_sel_hi:[1,0,1]
	v_and_b32_e32 v126, 0xffff0000, v124
	v_lshlrev_b32_e32 v127, 16, v124
	v_and_b32_e32 v142, 0xffff0000, v128
	v_lshlrev_b32_e32 v143, 16, v128
	v_and_b32_e32 v124, 0xffff0000, v125
	v_lshlrev_b32_e32 v125, 16, v125
	v_and_b32_e32 v128, 0xffff0000, v129
	v_lshlrev_b32_e32 v129, 16, v129
	v_pk_fma_f32 v[126:127], v[142:143], s[16:17], v[126:127] op_sel_hi:[1,0,1]
	v_pk_fma_f32 v[128:129], v[128:129], s[16:17], v[124:125] op_sel_hi:[1,0,1]
	v_and_b32_e32 v124, 0xffff0000, v114
	v_lshlrev_b32_e32 v125, 16, v114
	v_and_b32_e32 v142, 0xffff0000, v118
	v_lshlrev_b32_e32 v143, 16, v118
	v_and_b32_e32 v114, 0xffff0000, v115
	v_lshlrev_b32_e32 v115, 16, v115
	v_and_b32_e32 v118, 0xffff0000, v119
	v_lshlrev_b32_e32 v119, 16, v119
	v_pk_fma_f32 v[124:125], v[142:143], s[16:17], v[124:125] op_sel_hi:[1,0,1]
	v_pk_fma_f32 v[142:143], v[118:119], s[16:17], v[114:115] op_sel_hi:[1,0,1]
	v_and_b32_e32 v114, 0xffff0000, v116
	v_lshlrev_b32_e32 v115, 16, v116
	v_and_b32_e32 v118, 0xffff0000, v120
	v_lshlrev_b32_e32 v119, 16, v120
	v_pk_fma_f32 v[144:145], v[118:119], s[16:17], v[114:115] op_sel_hi:[1,0,1]
	v_and_b32_e32 v114, 0xffff0000, v117
	v_lshlrev_b32_e32 v115, 16, v117
	v_and_b32_e32 v116, 0xffff0000, v121
	v_lshlrev_b32_e32 v117, 16, v121
	v_pk_fma_f32 v[116:117], v[116:117], s[16:17], v[114:115] op_sel_hi:[1,0,1]
	v_and_b32_e32 v114, 0xffff0000, v106
	v_lshlrev_b32_e32 v115, 16, v106
	v_and_b32_e32 v118, 0xffff0000, v110
	v_lshlrev_b32_e32 v119, 16, v110
	v_and_b32_e32 v106, 0xffff0000, v107
	v_lshlrev_b32_e32 v107, 16, v107
	v_and_b32_e32 v110, 0xffff0000, v111
	v_lshlrev_b32_e32 v111, 16, v111
	v_pk_fma_f32 v[114:115], v[118:119], s[16:17], v[114:115] op_sel_hi:[1,0,1]
	v_pk_fma_f32 v[118:119], v[110:111], s[16:17], v[106:107] op_sel_hi:[1,0,1]
	v_and_b32_e32 v106, 0xffff0000, v108
	v_lshlrev_b32_e32 v107, 16, v108
	v_and_b32_e32 v110, 0xffff0000, v112
	v_lshlrev_b32_e32 v111, 16, v112
	v_pk_fma_f32 v[120:121], v[110:111], s[16:17], v[106:107] op_sel_hi:[1,0,1]
	v_and_b32_e32 v106, 0xffff0000, v109
	v_lshlrev_b32_e32 v107, 16, v109
	v_and_b32_e32 v108, 0xffff0000, v113
	v_lshlrev_b32_e32 v109, 16, v113
	v_pk_fma_f32 v[146:147], v[108:109], s[16:17], v[106:107] op_sel_hi:[1,0,1]
	v_and_b32_e32 v106, 0xffff0000, v98
	v_lshlrev_b32_e32 v107, 16, v98
	v_and_b32_e32 v108, 0xffff0000, v102
	v_lshlrev_b32_e32 v109, 16, v102
	v_and_b32_e32 v98, 0xffff0000, v99
	v_lshlrev_b32_e32 v99, 16, v99
	v_and_b32_e32 v102, 0xffff0000, v103
	v_lshlrev_b32_e32 v103, 16, v103
	v_pk_fma_f32 v[150:151], v[102:103], s[16:17], v[98:99] op_sel_hi:[1,0,1]
	v_and_b32_e32 v98, 0xffff0000, v100
	v_lshlrev_b32_e32 v99, 16, v100
	v_and_b32_e32 v102, 0xffff0000, v104
	v_lshlrev_b32_e32 v103, 16, v104
	v_pk_fma_f32 v[152:153], v[102:103], s[16:17], v[98:99] op_sel_hi:[1,0,1]
	v_and_b32_e32 v98, 0xffff0000, v101
	v_lshlrev_b32_e32 v99, 16, v101
	v_and_b32_e32 v100, 0xffff0000, v105
	v_lshlrev_b32_e32 v101, 16, v105
	v_pk_fma_f32 v[148:149], v[108:109], s[16:17], v[106:107] op_sel_hi:[1,0,1]
	v_pk_fma_f32 v[154:155], v[100:101], s[16:17], v[98:99] op_sel_hi:[1,0,1]
	v_cmp_lt_i32_e32 vcc, s18, v156
	s_and_saveexec_b64 s[10:11], vcc
	s_cbranch_execz .LBB0_1776
; __device__ __forceinline__ void ph_ln(const Args& a, int L, int which, bool final_, bool split, bool wr_x, bool res_inputs, int nblk, int b) {
;     ...
;         if (split && r >= MP) {
; #pragma unroll
;             for (int p = 0; p < 3; ++p) { const u32x4* pr = (const u32x4*)(P + ((size_t)p * MS + (r - MP)) * D) + lane;
; #pragma unroll
;                 for (int j = 0; j < 4; ++j) { const u32x4 w = pr[64 * j];
; #pragma unroll
;                     for (int e = 0; e < 4; ++e) { v[j][2 * e] += lo(w[e]); v[j][2 * e + 1] += hi(w[e]); } } } }
	v_add_u32_e32 v130, 0xffffe000, v156
	v_lshlrev_b64 v[98:99], 12, v[130:131]
	v_lshl_add_u64 v[98:99], v[134:135], 0, v[98:99]
	v_add_co_u32_e32 v100, vcc, s19, v98
	global_load_dwordx4 v[160:163], v[98:99], off nt
	global_load_dwordx4 v[106:109], v[98:99], off offset:1024 nt
	v_addc_co_u32_e32 v101, vcc, 0, v99, vcc
	global_load_dwordx4 v[164:167], v[100:101], off nt
	global_load_dwordx4 v[110:113], v[100:101], off offset:1024 nt
	v_add_co_u32_e32 v188, vcc, s20, v98
	s_waitcnt vmcnt(3)
	v_and_b32_e32 v192, 0xffff0000, v160
	v_addc_co_u32_e32 v189, vcc, 0, v99, vcc
	global_load_dwordx4 v[168:171], v[188:189], off nt
	global_load_dwordx4 v[172:175], v[188:189], off offset:1024 nt
	global_load_dwordx4 v[176:179], v[98:99], off offset:2048 nt
	global_load_dwordx4 v[180:183], v[100:101], off offset:2048 nt
	global_load_dwordx4 v[102:105], v[98:99], off offset:3072 nt
	s_nop 0
	global_load_dwordx4 v[98:101], v[100:101], off offset:3072 nt
	s_nop 0
	global_load_dwordx4 v[184:187], v[188:189], off offset:2048 nt
	s_nop 0
	global_load_dwordx4 v[188:191], v[188:189], off offset:3072 nt
	v_lshlrev_b32_e32 v193, 16, v160
	v_and_b32_e32 v160, 0xffff0000, v161
	v_lshlrev_b32_e32 v161, 16, v161
	v_and_b32_e32 v194, 0xffff0000, v162
	v_lshlrev_b32_e32 v195, 16, v162
	v_and_b32_e32 v162, 0xffff0000, v163
	v_lshlrev_b32_e32 v163, 16, v163
	s_waitcnt vmcnt(10)
	v_and_b32_e32 v196, 0xffff0000, v106
	v_lshlrev_b32_e32 v197, 16, v106
	v_and_b32_e32 v106, 0xffff0000, v107
	v_lshlrev_b32_e32 v107, 16, v107
	v_and_b32_e32 v198, 0xffff0000, v108
	v_lshlrev_b32_e32 v199, 16, v108
	v_pk_add_f32 v[122:123], v[122:123], v[160:161]
	v_pk_add_f32 v[128:129], v[128:129], v[162:163]
	v_pk_add_f32 v[106:107], v[142:143], v[106:107]
	v_pk_add_f32 v[142:143], v[144:145], v[198:199]
	s_waitcnt vmcnt(9)
	v_and_b32_e32 v144, 0xffff0000, v164
	v_lshlrev_b32_e32 v145, 16, v164
	v_and_b32_e32 v160, 0xffff0000, v165
	v_lshlrev_b32_e32 v161, 16, v165
	v_and_b32_e32 v162, 0xffff0000, v166
	v_lshlrev_b32_e32 v163, 16, v166
	v_and_b32_e32 v164, 0xffff0000, v167
	v_lshlrev_b32_e32 v165, 16, v167
	s_waitcnt vmcnt(8)
	v_and_b32_e32 v166, 0xffff0000, v110
	v_lshlrev_b32_e32 v167, 16, v110
	v_and_b32_e32 v110, 0xffff0000, v111
	v_lshlrev_b32_e32 v111, 16, v111
	v_pk_add_f32 v[140:141], v[140:141], v[192:193]
	v_and_b32_e32 v192, 0xffff0000, v112
	v_lshlrev_b32_e32 v193, 16, v112
	v_pk_add_f32 v[106:107], v[106:107], v[110:111]
	v_pk_add_f32 v[140:141], v[140:141], v[144:145]
	v_pk_add_f32 v[122:123], v[122:123], v[160:161]
	v_and_b32_e32 v108, 0xffff0000, v113
	v_pk_add_f32 v[126:127], v[126:127], v[194:195]
	v_pk_add_f32 v[124:125], v[124:125], v[196:197]
	v_pk_add_f32 v[126:127], v[126:127], v[162:163]
	v_pk_add_f32 v[128:129], v[128:129], v[164:165]
	v_pk_add_f32 v[124:125], v[124:125], v[166:167]
	s_waitcnt vmcnt(7)
	v_and_b32_e32 v144, 0xffff0000, v168
	s_waitcnt vmcnt(6)
	v_and_b32_e32 v110, 0xffff0000, v173
	v_lshlrev_b32_e32 v111, 16, v173
	v_lshlrev_b32_e32 v145, 16, v168
	v_and_b32_e32 v160, 0xffff0000, v169
	v_lshlrev_b32_e32 v161, 16, v169
	v_pk_add_f32 v[168:169], v[142:143], v[192:193]
	v_pk_add_f32 v[142:143], v[106:107], v[110:111]
	v_and_b32_e32 v106, 0xffff0000, v109
	v_lshlrev_b32_e32 v107, 16, v109
	v_pk_add_f32 v[106:107], v[116:117], v[106:107]
	v_lshlrev_b32_e32 v109, 16, v113
	v_pk_add_f32 v[106:107], v[106:107], v[108:109]
	v_and_b32_e32 v108, 0xffff0000, v175
	v_lshlrev_b32_e32 v109, 16, v175
	v_pk_add_f32 v[116:117], v[106:107], v[108:109]
	s_waitcnt vmcnt(5)
	v_and_b32_e32 v106, 0xffff0000, v176
	v_lshlrev_b32_e32 v107, 16, v176
	v_pk_add_f32 v[106:107], v[114:115], v[106:107]
	s_waitcnt vmcnt(4)
	v_and_b32_e32 v108, 0xffff0000, v180
	v_lshlrev_b32_e32 v109, 16, v180
	v_pk_add_f32 v[106:107], v[106:107], v[108:109]
	s_waitcnt vmcnt(1)
	v_and_b32_e32 v108, 0xffff0000, v184
	v_lshlrev_b32_e32 v109, 16, v184
	v_pk_add_f32 v[114:115], v[106:107], v[108:109]
	v_and_b32_e32 v106, 0xffff0000, v177
	v_lshlrev_b32_e32 v107, 16, v177
	v_pk_add_f32 v[106:107], v[118:119], v[106:107]
	v_and_b32_e32 v108, 0xffff0000, v181
	v_lshlrev_b32_e32 v109, 16, v181
	v_pk_add_f32 v[106:107], v[106:107], v[108:109]
	v_and_b32_e32 v108, 0xffff0000, v185
	v_lshlrev_b32_e32 v109, 16, v185
	v_pk_add_f32 v[118:119], v[106:107], v[108:109]
	v_and_b32_e32 v106, 0xffff0000, v178
	v_lshlrev_b32_e32 v107, 16, v178
	v_pk_add_f32 v[106:107], v[120:121], v[106:107]
	v_and_b32_e32 v108, 0xffff0000, v182
	v_lshlrev_b32_e32 v109, 16, v182
	v_pk_add_f32 v[106:107], v[106:107], v[108:109]
	v_and_b32_e32 v108, 0xffff0000, v186
	v_lshlrev_b32_e32 v109, 16, v186
	v_pk_add_f32 v[120:121], v[106:107], v[108:109]
	v_and_b32_e32 v106, 0xffff0000, v179
	v_lshlrev_b32_e32 v107, 16, v179
	v_pk_add_f32 v[106:107], v[146:147], v[106:107]
	v_and_b32_e32 v108, 0xffff0000, v183
	v_lshlrev_b32_e32 v109, 16, v183
	v_pk_add_f32 v[106:107], v[106:107], v[108:109]
	v_and_b32_e32 v108, 0xffff0000, v187
	v_lshlrev_b32_e32 v109, 16, v187
	v_pk_add_f32 v[146:147], v[106:107], v[108:109]
	v_and_b32_e32 v106, 0xffff0000, v102
	v_lshlrev_b32_e32 v107, 16, v102
	v_and_b32_e32 v102, 0xffff0000, v103
	v_lshlrev_b32_e32 v103, 16, v103
	v_and_b32_e32 v108, 0xffff0000, v98
	v_lshlrev_b32_e32 v109, 16, v98
	v_pk_add_f32 v[102:103], v[150:151], v[102:103]
	v_and_b32_e32 v98, 0xffff0000, v99
	v_lshlrev_b32_e32 v99, 16, v99
	v_pk_add_f32 v[98:99], v[102:103], v[98:99]
	s_waitcnt vmcnt(0)
	v_and_b32_e32 v102, 0xffff0000, v189
	v_lshlrev_b32_e32 v103, 16, v189
	v_pk_add_f32 v[150:151], v[98:99], v[102:103]
	v_and_b32_e32 v98, 0xffff0000, v104
	v_lshlrev_b32_e32 v99, 16, v104
	v_pk_add_f32 v[98:99], v[152:153], v[98:99]
	v_and_b32_e32 v102, 0xffff0000, v100
	v_lshlrev_b32_e32 v103, 16, v100
	v_pk_add_f32 v[98:99], v[98:99], v[102:103]
	v_and_b32_e32 v102, 0xffff0000, v190
	v_lshlrev_b32_e32 v103, 16, v190
	v_pk_add_f32 v[152:153], v[98:99], v[102:103]
	v_and_b32_e32 v98, 0xffff0000, v105
	v_lshlrev_b32_e32 v99, 16, v105
	v_pk_add_f32 v[106:107], v[148:149], v[106:107]
	v_pk_add_f32 v[98:99], v[154:155], v[98:99]
	v_and_b32_e32 v100, 0xffff0000, v101
	v_lshlrev_b32_e32 v101, 16, v101
	v_and_b32_e32 v162, 0xffff0000, v170
	v_lshlrev_b32_e32 v163, 16, v170
	v_and_b32_e32 v164, 0xffff0000, v171
	v_lshlrev_b32_e32 v165, 16, v171
	v_and_b32_e32 v166, 0xffff0000, v172
	v_lshlrev_b32_e32 v167, 16, v172
	v_and_b32_e32 v170, 0xffff0000, v174
	v_lshlrev_b32_e32 v171, 16, v174
	v_pk_add_f32 v[106:107], v[106:107], v[108:109]
	v_and_b32_e32 v108, 0xffff0000, v188
	v_lshlrev_b32_e32 v109, 16, v188
	v_pk_add_f32 v[98:99], v[98:99], v[100:101]
	v_and_b32_e32 v100, 0xffff0000, v191
	v_lshlrev_b32_e32 v101, 16, v191
	v_pk_add_f32 v[140:141], v[140:141], v[144:145]
	v_pk_add_f32 v[122:123], v[122:123], v[160:161]
	v_pk_add_f32 v[126:127], v[126:127], v[162:163]
	v_pk_add_f32 v[128:129], v[128:129], v[164:165]
	v_pk_add_f32 v[124:125], v[124:125], v[166:167]
	v_pk_add_f32 v[144:145], v[168:169], v[170:171]
	v_pk_add_f32 v[148:149], v[106:107], v[108:109]
	v_pk_add_f32 v[154:155], v[98:99], v[100:101]
	s_branch .LBB0_1776

; __device__ __forceinline__ void ph_ln(const Args& a, int L, int which, bool final_, bool split, bool wr_x, bool res_inputs, int nblk, int b) {
;     ...
;     auto ldrow = [&](int r) { const u32x4* zr = (const u32x4*)(Z + (size_t)r * D) + lane;
; #pragma unroll
;         for (int j = 0; j < 4; ++j) zc[j] = zr[64 * j];
;         if (!res_inputs) { const u32x4* xr = (const u32x4*)(XB + (size_t)r * D) + lane;
; #pragma unroll
;             for (int j = 0; j < 4; ++j) xc[j] = xr[64 * j]; } };
;     if (gw < M) ldrow(gw);
;     for (int r = gw; r < M; r += ngw) {
;         float v[4][8];
; #pragma unroll
;         for (int j = 0; j < 4; ++j)
; #pragma unroll
;             for (int e = 0; e < 4; ++e) { v[j][2 * e] = lo(zc[j][e]); v[j][2 * e + 1] = hi(zc[j][e]); }
;         if (!res_inputs) {
; #pragma unroll
;             for (int j = 0; j < 4; ++j)
; #pragma unroll
;                 for (int e = 0; e < 4; ++e) { v[j][2 * e] += ALPHA * lo(xc[j][e]); v[j][2 * e + 1] += ALPHA * hi(xc[j][e]); } }
.LBB0_1968:
	v_add_u32_e32 v158, s74, v156
	v_cmp_gt_i32_e32 vcc, s1, v158
	v_cmp_lt_i32_e64 s[8:9], s15, v158
	s_and_saveexec_b64 s[4:5], vcc
	s_cbranch_execz .LBB0_1970
	v_lshl_add_u64 v[82:83], s[68:69], 0, v[136:137]
	v_add_co_u32_e32 v66, vcc, 0x1e100000, v82
	s_nop 1
	v_addc_co_u32_e32 v67, vcc, 0, v83, vcc
	v_add_co_u32_e32 v82, vcc, 0x1b900000, v82
	global_load_dwordx4 v[78:81], v[66:67], off nt
	global_load_dwordx4 v[74:77], v[66:67], off offset:1024 nt
	global_load_dwordx4 v[70:73], v[66:67], off offset:2048 nt
	s_nop 0
	global_load_dwordx4 v[66:69], v[66:67], off offset:3072 nt
	v_addc_co_u32_e32 v83, vcc, 0, v83, vcc
	global_load_dwordx4 v[94:97], v[82:83], off nt
	global_load_dwordx4 v[90:93], v[82:83], off offset:1024 nt
	global_load_dwordx4 v[86:89], v[82:83], off offset:2048 nt
	s_nop 0
	global_load_dwordx4 v[82:85], v[82:83], off offset:3072 nt
.LBB0_1970:
	s_or_b64 exec, exec, s[4:5]
	v_and_b32_e32 v140, 0xffff0000, v122
	v_lshlrev_b32_e32 v141, 16, v122
	v_and_b32_e32 v142, 0xffff0000, v126
	v_lshlrev_b32_e32 v143, 16, v126
	v_and_b32_e32 v122, 0xffff0000, v123
	v_lshlrev_b32_e32 v123, 16, v123
	v_and_b32_e32 v126, 0xffff0000, v127
	v_lshlrev_b32_e32 v127, 16, v127
	v_pk_fma_f32 v[140:141], v[142:143], s[14:15], v[140:141] op_sel_hi:[1,0,1]
	v_pk_fma_f32 v[122:123], v[126:127], s[14:15], v[122:123] op_sel_hi:[1,0,1]
	v_and_b32_e32 v126, 0xffff0000, v124
	v_lshlrev_b32_e32 v127, 16, v124
	v_and_b32_e32 v142, 0xffff0000, v128
	v_lshlrev_b32_e32 v143, 16, v128
	v_and_b32_e32 v124, 0xffff0000, v125
	v_lshlrev_b32_e32 v125, 16, v125
	v_and_b32_e32 v128, 0xffff0000, v129
	v_lshlrev_b32_e32 v129, 16, v129
	v_pk_fma_f32 v[126:127], v[142:143], s[14:15], v[126:127] op_sel_hi:[1,0,1]
	v_pk_fma_f32 v[128:129], v[128:129], s[14:15], v[124:125] op_sel_hi:[1,0,1]
	v_and_b32_e32 v124, 0xffff0000, v114
	v_lshlrev_b32_e32 v125, 16, v114
	v_and_b32_e32 v142, 0xffff0000, v118
	v_lshlrev_b32_e32 v143, 16, v118
	v_and_b32_e32 v114, 0xffff0000, v115
	v_lshlrev_b32_e32 v115, 16, v115
	v_and_b32_e32 v118, 0xffff0000, v119
	v_lshlrev_b32_e32 v119, 16, v119
	v_pk_fma_f32 v[124:125], v[142:143], s[14:15], v[124:125] op_sel_hi:[1,0,1]
	v_pk_fma_f32 v[142:143], v[118:119], s[14:15], v[114:115] op_sel_hi:[1,0,1]
	v_and_b32_e32 v114, 0xffff0000, v116
	v_lshlrev_b32_e32 v115, 16, v116
	v_and_b32_e32 v118, 0xffff0000, v120
	v_lshlrev_b32_e32 v119, 16, v120
	v_pk_fma_f32 v[144:145], v[118:119], s[14:15], v[114:115] op_sel_hi:[1,0,1]
	v_and_b32_e32 v114, 0xffff0000, v117
	v_lshlrev_b32_e32 v115, 16, v117
	v_and_b32_e32 v116, 0xffff0000, v121
	v_lshlrev_b32_e32 v117, 16, v121
	v_pk_fma_f32 v[116:117], v[116:117], s[14:15], v[114:115] op_sel_hi:[1,0,1]
	v_and_b32_e32 v114, 0xffff0000, v106
	v_lshlrev_b32_e32 v115, 16, v106
	v_and_b32_e32 v118, 0xffff0000, v110
	v_lshlrev_b32_e32 v119, 16, v110
	v_and_b32_e32 v106, 0xffff0000, v107
	v_lshlrev_b32_e32 v107, 16, v107
	v_and_b32_e32 v110, 0xffff0000, v111
	v_lshlrev_b32_e32 v111, 16, v111
	v_pk_fma_f32 v[114:115], v[118:119], s[14:15], v[114:115] op_sel_hi:[1,0,1]
	v_pk_fma_f32 v[118:119], v[110:111], s[14:15], v[106:107] op_sel_hi:[1,0,1]
	v_and_b32_e32 v106, 0xffff0000, v108
	v_lshlrev_b32_e32 v107, 16, v108
	v_and_b32_e32 v110, 0xffff0000, v112
	v_lshlrev_b32_e32 v111, 16, v112
	v_pk_fma_f32 v[120:121], v[110:111], s[14:15], v[106:107] op_sel_hi:[1,0,1]
	v_and_b32_e32 v106, 0xffff0000, v109
	v_lshlrev_b32_e32 v107, 16, v109
	v_and_b32_e32 v108, 0xffff0000, v113
	v_lshlrev_b32_e32 v109, 16, v113
	v_pk_fma_f32 v[146:147], v[108:109], s[14:15], v[106:107] op_sel_hi:[1,0,1]
	v_and_b32_e32 v106, 0xffff0000, v98
	v_lshlrev_b32_e32 v107, 16, v98
	v_and_b32_e32 v108, 0xffff0000, v102
	v_lshlrev_b32_e32 v109, 16, v102
	v_and_b32_e32 v98, 0xffff0000, v99
	v_lshlrev_b32_e32 v99, 16, v99
	v_and_b32_e32 v102, 0xffff0000, v103
	v_lshlrev_b32_e32 v103, 16, v103
	v_pk_fma_f32 v[150:151], v[102:103], s[14:15], v[98:99] op_sel_hi:[1,0,1]
	v_and_b32_e32 v98, 0xffff0000, v100
	v_lshlrev_b32_e32 v99, 16, v100
	v_and_b32_e32 v102, 0xffff0000, v104
	v_lshlrev_b32_e32 v103, 16, v104
	s_and_b64 s[4:5], exec, s[8:9]
	v_pk_fma_f32 v[152:153], v[102:103], s[14:15], v[98:99] op_sel_hi:[1,0,1]
	v_and_b32_e32 v98, 0xffff0000, v101
	v_lshlrev_b32_e32 v99, 16, v101
	v_and_b32_e32 v100, 0xffff0000, v105
	v_lshlrev_b32_e32 v101, 16, v105
	s_or_b64 s[12:13], s[4:5], s[12:13]
	v_pk_fma_f32 v[148:149], v[108:109], s[14:15], v[106:107] op_sel_hi:[1,0,1]
	v_pk_fma_f32 v[154:155], v[100:101], s[14:15], v[98:99] op_sel_hi:[1,0,1]
	v_cmp_lt_i32_e32 vcc, s16, v156
	s_and_saveexec_b64 s[8:9], vcc
	s_cbranch_execz .LBB0_1967
; __device__ __forceinline__ void ph_ln(const Args& a, int L, int which, bool final_, bool split, bool wr_x, bool res_inputs, int nblk, int b) {
;     ...
;         if (split && r >= MP) {
; #pragma unroll
;             for (int p = 0; p < 3; ++p) { const u32x4* pr = (const u32x4*)(P + ((size_t)p * MS + (r - MP)) * D) + lane;
; #pragma unroll
;                 for (int j = 0; j < 4; ++j) { const u32x4 w = pr[64 * j];
; #pragma unroll
;                     for (int e = 0; e < 4; ++e) { v[j][2 * e] += lo(w[e]); v[j][2 * e + 1] += hi(w[e]); } } } }
	v_add_u32_e32 v130, 0xffffe000, v156
	v_lshlrev_b64 v[98:99], 12, v[130:131]
	v_lshl_add_u64 v[98:99], v[132:133], 0, v[98:99]
	v_add_co_u32_e32 v100, vcc, s17, v98
	global_load_dwordx4 v[160:163], v[98:99], off nt
	global_load_dwordx4 v[106:109], v[98:99], off offset:1024 nt
	v_addc_co_u32_e32 v101, vcc, 0, v99, vcc
	global_load_dwordx4 v[164:167], v[100:101], off nt
	global_load_dwordx4 v[110:113], v[100:101], off offset:1024 nt
	v_add_co_u32_e32 v188, vcc, s18, v98
	s_waitcnt vmcnt(3)
	v_and_b32_e32 v192, 0xffff0000, v160
	v_addc_co_u32_e32 v189, vcc, 0, v99, vcc
	global_load_dwordx4 v[168:171], v[188:189], off nt
	global_load_dwordx4 v[172:175], v[188:189], off offset:1024 nt
	global_load_dwordx4 v[176:179], v[98:99], off offset:2048 nt
	global_load_dwordx4 v[180:183], v[100:101], off offset:2048 nt
	global_load_dwordx4 v[102:105], v[98:99], off offset:3072 nt
	s_nop 0
	global_load_dwordx4 v[98:101], v[100:101], off offset:3072 nt
	s_nop 0
	global_load_dwordx4 v[184:187], v[188:189], off offset:2048 nt
	s_nop 0
	global_load_dwordx4 v[188:191], v[188:189], off offset:3072 nt
	v_lshlrev_b32_e32 v193, 16, v160
	v_and_b32_e32 v160, 0xffff0000, v161
	v_lshlrev_b32_e32 v161, 16, v161
	v_and_b32_e32 v194, 0xffff0000, v162
	v_lshlrev_b32_e32 v195, 16, v162
	v_and_b32_e32 v162, 0xffff0000, v163
	v_lshlrev_b32_e32 v163, 16, v163
	s_waitcnt vmcnt(10)
	v_and_b32_e32 v196, 0xffff0000, v106
	v_lshlrev_b32_e32 v197, 16, v106
	v_and_b32_e32 v106, 0xffff0000, v107
	v_lshlrev_b32_e32 v107, 16, v107
	v_and_b32_e32 v198, 0xffff0000, v108
	v_lshlrev_b32_e32 v199, 16, v108
	v_pk_add_f32 v[122:123], v[122:123], v[160:161]
	v_pk_add_f32 v[128:129], v[128:129], v[162:163]
	v_pk_add_f32 v[106:107], v[142:143], v[106:107]
	v_pk_add_f32 v[142:143], v[144:145], v[198:199]
	s_waitcnt vmcnt(9)
	v_and_b32_e32 v144, 0xffff0000, v164
	v_lshlrev_b32_e32 v145, 16, v164
	v_and_b32_e32 v160, 0xffff0000, v165
	v_lshlrev_b32_e32 v161, 16, v165
	v_and_b32_e32 v162, 0xffff0000, v166
	v_lshlrev_b32_e32 v163, 16, v166
	v_and_b32_e32 v164, 0xffff0000, v167
	v_lshlrev_b32_e32 v165, 16, v167
	s_waitcnt vmcnt(8)
	v_and_b32_e32 v166, 0xffff0000, v110
	v_lshlrev_b32_e32 v167, 16, v110
	v_and_b32_e32 v110, 0xffff0000, v111
	v_lshlrev_b32_e32 v111, 16, v111
	v_pk_add_f32 v[140:141], v[140:141], v[192:193]
	v_and_b32_e32 v192, 0xffff0000, v112
	v_lshlrev_b32_e32 v193, 16, v112
	v_pk_add_f32 v[106:107], v[106:107], v[110:111]
	v_pk_add_f32 v[140:141], v[140:141], v[144:145]
	v_pk_add_f32 v[122:123], v[122:123], v[160:161]
	v_and_b32_e32 v108, 0xffff0000, v113
	v_pk_add_f32 v[126:127], v[126:127], v[194:195]
	v_pk_add_f32 v[124:125], v[124:125], v[196:197]
	v_pk_add_f32 v[126:127], v[126:127], v[162:163]
	v_pk_add_f32 v[128:129], v[128:129], v[164:165]
	v_pk_add_f32 v[124:125], v[124:125], v[166:167]
	s_waitcnt vmcnt(7)
	v_and_b32_e32 v144, 0xffff0000, v168
	s_waitcnt vmcnt(6)
	v_and_b32_e32 v110, 0xffff0000, v173
	v_lshlrev_b32_e32 v111, 16, v173
	v_lshlrev_b32_e32 v145, 16, v168
	v_and_b32_e32 v160, 0xffff0000, v169
	v_lshlrev_b32_e32 v161, 16, v169
	v_pk_add_f32 v[168:169], v[142:143], v[192:193]
	v_pk_add_f32 v[142:143], v[106:107], v[110:111]
	v_and_b32_e32 v106, 0xffff0000, v109
	v_lshlrev_b32_e32 v107, 16, v109
	v_pk_add_f32 v[106:107], v[116:117], v[106:107]
	v_lshlrev_b32_e32 v109, 16, v113
	v_pk_add_f32 v[106:107], v[106:107], v[108:109]
	v_and_b32_e32 v108, 0xffff0000, v175
	v_lshlrev_b32_e32 v109, 16, v175
	v_pk_add_f32 v[116:117], v[106:107], v[108:109]
	s_waitcnt vmcnt(5)
	v_and_b32_e32 v106, 0xffff0000, v176
	v_lshlrev_b32_e32 v107, 16, v176
	v_pk_add_f32 v[106:107], v[114:115], v[106:107]
	s_waitcnt vmcnt(4)
	v_and_b32_e32 v108, 0xffff0000, v180
	v_lshlrev_b32_e32 v109, 16, v180
	v_pk_add_f32 v[106:107], v[106:107], v[108:109]
	s_waitcnt vmcnt(1)
	v_and_b32_e32 v108, 0xffff0000, v184
	v_lshlrev_b32_e32 v109, 16, v184
	v_pk_add_f32 v[114:115], v[106:107], v[108:109]
	v_and_b32_e32 v106, 0xffff0000, v177
	v_lshlrev_b32_e32 v107, 16, v177
	v_pk_add_f32 v[106:107], v[118:119], v[106:107]
	v_and_b32_e32 v108, 0xffff0000, v181
	v_lshlrev_b32_e32 v109, 16, v181
	v_pk_add_f32 v[106:107], v[106:107], v[108:109]
	v_and_b32_e32 v108, 0xffff0000, v185
	v_lshlrev_b32_e32 v109, 16, v185
	v_pk_add_f32 v[118:119], v[106:107], v[108:109]
	v_and_b32_e32 v106, 0xffff0000, v178
	v_lshlrev_b32_e32 v107, 16, v178
	v_pk_add_f32 v[106:107], v[120:121], v[106:107]
	v_and_b32_e32 v108, 0xffff0000, v182
	v_lshlrev_b32_e32 v109, 16, v182
	v_pk_add_f32 v[106:107], v[106:107], v[108:109]
	v_and_b32_e32 v108, 0xffff0000, v186
	v_lshlrev_b32_e32 v109, 16, v186
	v_pk_add_f32 v[120:121], v[106:107], v[108:109]
	v_and_b32_e32 v106, 0xffff0000, v179
	v_lshlrev_b32_e32 v107, 16, v179
	v_pk_add_f32 v[106:107], v[146:147], v[106:107]
	v_and_b32_e32 v108, 0xffff0000, v183
	v_lshlrev_b32_e32 v109, 16, v183
	v_pk_add_f32 v[106:107], v[106:107], v[108:109]
	v_and_b32_e32 v108, 0xffff0000, v187
	v_lshlrev_b32_e32 v109, 16, v187
	v_pk_add_f32 v[146:147], v[106:107], v[108:109]
	v_and_b32_e32 v106, 0xffff0000, v102
	v_lshlrev_b32_e32 v107, 16, v102
	v_and_b32_e32 v102, 0xffff0000, v103
	v_lshlrev_b32_e32 v103, 16, v103
	v_and_b32_e32 v108, 0xffff0000, v98
	v_lshlrev_b32_e32 v109, 16, v98
	v_pk_add_f32 v[102:103], v[150:151], v[102:103]
	v_and_b32_e32 v98, 0xffff0000, v99
	v_lshlrev_b32_e32 v99, 16, v99
	v_pk_add_f32 v[98:99], v[102:103], v[98:99]
	s_waitcnt vmcnt(0)
	v_and_b32_e32 v102, 0xffff0000, v189
	v_lshlrev_b32_e32 v103, 16, v189
	v_pk_add_f32 v[150:151], v[98:99], v[102:103]
	v_and_b32_e32 v98, 0xffff0000, v104
	v_lshlrev_b32_e32 v99, 16, v104
	v_pk_add_f32 v[98:99], v[152:153], v[98:99]
	v_and_b32_e32 v102, 0xffff0000, v100
	v_lshlrev_b32_e32 v103, 16, v100
	v_pk_add_f32 v[98:99], v[98:99], v[102:103]
	v_and_b32_e32 v102, 0xffff0000, v190
	v_lshlrev_b32_e32 v103, 16, v190
	v_pk_add_f32 v[152:153], v[98:99], v[102:103]
	v_and_b32_e32 v98, 0xffff0000, v105
	v_lshlrev_b32_e32 v99, 16, v105
	v_pk_add_f32 v[106:107], v[148:149], v[106:107]
	v_pk_add_f32 v[98:99], v[154:155], v[98:99]
	v_and_b32_e32 v100, 0xffff0000, v101
	v_lshlrev_b32_e32 v101, 16, v101
	v_and_b32_e32 v162, 0xffff0000, v170
	v_lshlrev_b32_e32 v163, 16, v170
	v_and_b32_e32 v164, 0xffff0000, v171
	v_lshlrev_b32_e32 v165, 16, v171
	v_and_b32_e32 v166, 0xffff0000, v172
	v_lshlrev_b32_e32 v167, 16, v172
	v_and_b32_e32 v170, 0xffff0000, v174
	v_lshlrev_b32_e32 v171, 16, v174
	v_pk_add_f32 v[106:107], v[106:107], v[108:109]
	v_and_b32_e32 v108, 0xffff0000, v188
	v_lshlrev_b32_e32 v109, 16, v188
	v_pk_add_f32 v[98:99], v[98:99], v[100:101]
	v_and_b32_e32 v100, 0xffff0000, v191
	v_lshlrev_b32_e32 v101, 16, v191
	v_pk_add_f32 v[140:141], v[140:141], v[144:145]
	v_pk_add_f32 v[122:123], v[122:123], v[160:161]
	v_pk_add_f32 v[126:127], v[126:127], v[162:163]
	v_pk_add_f32 v[128:129], v[128:129], v[164:165]
	v_pk_add_f32 v[124:125], v[124:125], v[166:167]
	v_pk_add_f32 v[144:145], v[168:169], v[170:171]
	v_pk_add_f32 v[148:149], v[106:107], v[108:109]
	v_pk_add_f32 v[154:155], v[98:99], v[100:101]
	s_branch .LBB0_1967

; __device__ __forceinline__ void ph_ln(const Args& a, int L, int which, bool final_, bool split, bool wr_x, bool res_inputs, int nblk, int b) {
;     ...
;     auto ldrow = [&](int r) { const u32x4* zr = (const u32x4*)(Z + (size_t)r * D) + lane;
; #pragma unroll
;         for (int j = 0; j < 4; ++j) zc[j] = zr[64 * j];
;         if (!res_inputs) { const u32x4* xr = (const u32x4*)(XB + (size_t)r * D) + lane;
; #pragma unroll
;             for (int j = 0; j < 4; ++j) xc[j] = xr[64 * j]; } };
.LBB0_2200:
	v_add_u32_e32 v130, s74, v130
	v_cmp_lt_i32_e64 s[2:3], s4, v130
	v_cmp_gt_i32_e32 vcc, s1, v130
	s_or_b64 s[12:13], s[2:3], s[12:13]
	s_and_saveexec_b64 s[2:3], vcc
	s_cbranch_execz .LBB0_2199
	v_lshl_add_u64 v[82:83], v[138:139], 0, v[134:135]
	v_add_co_u32_e32 v84, vcc, 0x1e100000, v82
	s_nop 1
	v_addc_co_u32_e32 v85, vcc, 0, v83, vcc
	v_add_co_u32_e32 v82, vcc, 0x1b900000, v82
	global_load_dwordx4 v[78:81], v[84:85], off nt
	global_load_dwordx4 v[74:77], v[84:85], off offset:1024 nt
	global_load_dwordx4 v[70:73], v[84:85], off offset:2048 nt
	global_load_dwordx4 v[66:69], v[84:85], off offset:3072 nt
	v_addc_co_u32_e32 v83, vcc, 0, v83, vcc
	global_load_dwordx4 v[94:97], v[82:83], off nt
	global_load_dwordx4 v[90:93], v[82:83], off offset:1024 nt
	global_load_dwordx4 v[86:89], v[82:83], off offset:2048 nt
	s_nop 0
	global_load_dwordx4 v[82:85], v[82:83], off offset:3072 nt
	s_branch .LBB0_2199

; __device__ __forceinline__ void ph_ln(const Args& a, int L, int which, bool final_, bool split, bool wr_x, bool res_inputs, int nblk, int b) {
;     ...
;     auto ldrow = [&](int r) { const u32x4* zr = (const u32x4*)(Z + (size_t)r * D) + lane;
; #pragma unroll
;         for (int j = 0; j < 4; ++j) zc[j] = zr[64 * j];
;         if (!res_inputs) { const u32x4* xr = (const u32x4*)(XB + (size_t)r * D) + lane;
; #pragma unroll
;             for (int j = 0; j < 4; ++j) xc[j] = xr[64 * j]; } };
;     if (gw < M) ldrow(gw);
;     for (int r = gw; r < M; r += ngw) {
;         float v[4][8];
; #pragma unroll
;         for (int j = 0; j < 4; ++j)
; #pragma unroll
;             for (int e = 0; e < 4; ++e) { v[j][2 * e] = lo(zc[j][e]); v[j][2 * e + 1] = hi(zc[j][e]); }
;         if (!res_inputs) {
; #pragma unroll
;             for (int j = 0; j < 4; ++j)
; #pragma unroll
;                 for (int e = 0; e < 4; ++e) { v[j][2 * e] += ALPHA * lo(xc[j][e]); v[j][2 * e + 1] += ALPHA * hi(xc[j][e]); } }
.LBB0_2389:
	v_add_u32_e32 v155, s74, v152
	v_cmp_gt_i32_e32 vcc, s11, v155
	v_cmp_lt_i32_e64 s[0:1], s12, v155
	s_and_saveexec_b64 s[2:3], vcc
	s_cbranch_execz .LBB0_2391
	v_add_co_u32_e32 v80, vcc, 0xfd800000, v134
	global_load_dwordx4 v[76:79], v[134:135], off offset:-3072 nt
	global_load_dwordx4 v[72:75], v[134:135], off offset:-2048 nt
	global_load_dwordx4 v[68:71], v[134:135], off offset:-1024 nt
	global_load_dwordx4 v[64:67], v[134:135], off nt
	v_addc_co_u32_e32 v81, vcc, -1, v135, vcc
	global_load_dwordx4 v[92:95], v[80:81], off offset:-3072 nt
	global_load_dwordx4 v[88:91], v[80:81], off offset:-2048 nt
	global_load_dwordx4 v[84:87], v[80:81], off offset:-1024 nt
	s_nop 0
	global_load_dwordx4 v[80:83], v[80:81], off nt
.LBB0_2391:
	s_or_b64 exec, exec, s[2:3]
	v_and_b32_e32 v136, 0xffff0000, v120
	v_lshlrev_b32_e32 v137, 16, v120
	v_and_b32_e32 v138, 0xffff0000, v124
	v_lshlrev_b32_e32 v139, 16, v124
	v_and_b32_e32 v120, 0xffff0000, v121
	v_lshlrev_b32_e32 v121, 16, v121
	v_and_b32_e32 v124, 0xffff0000, v125
	v_lshlrev_b32_e32 v125, 16, v125
	v_pk_fma_f32 v[136:137], v[138:139], s[10:11], v[136:137] op_sel_hi:[1,0,1]
	v_pk_fma_f32 v[120:121], v[124:125], s[10:11], v[120:121] op_sel_hi:[1,0,1]
	v_and_b32_e32 v124, 0xffff0000, v122
	v_lshlrev_b32_e32 v125, 16, v122
	v_and_b32_e32 v138, 0xffff0000, v126
	v_lshlrev_b32_e32 v139, 16, v126
	v_and_b32_e32 v122, 0xffff0000, v123
	v_lshlrev_b32_e32 v123, 16, v123
	v_and_b32_e32 v126, 0xffff0000, v127
	v_lshlrev_b32_e32 v127, 16, v127
	v_pk_fma_f32 v[124:125], v[138:139], s[10:11], v[124:125] op_sel_hi:[1,0,1]
	v_pk_fma_f32 v[126:127], v[126:127], s[10:11], v[122:123] op_sel_hi:[1,0,1]
	v_and_b32_e32 v122, 0xffff0000, v112
	v_lshlrev_b32_e32 v123, 16, v112
	v_and_b32_e32 v138, 0xffff0000, v116
	v_lshlrev_b32_e32 v139, 16, v116
	v_and_b32_e32 v112, 0xffff0000, v113
	v_lshlrev_b32_e32 v113, 16, v113
	v_and_b32_e32 v116, 0xffff0000, v117
	v_lshlrev_b32_e32 v117, 16, v117
	v_pk_fma_f32 v[122:123], v[138:139], s[10:11], v[122:123] op_sel_hi:[1,0,1]
	v_pk_fma_f32 v[138:139], v[116:117], s[10:11], v[112:113] op_sel_hi:[1,0,1]
	v_and_b32_e32 v112, 0xffff0000, v114
	v_lshlrev_b32_e32 v113, 16, v114
	v_and_b32_e32 v116, 0xffff0000, v118
	v_lshlrev_b32_e32 v117, 16, v118
	v_pk_fma_f32 v[142:143], v[116:117], s[10:11], v[112:113] op_sel_hi:[1,0,1]
	v_and_b32_e32 v112, 0xffff0000, v115
	v_lshlrev_b32_e32 v113, 16, v115
	v_and_b32_e32 v114, 0xffff0000, v119
	v_lshlrev_b32_e32 v115, 16, v119
	v_pk_fma_f32 v[114:115], v[114:115], s[10:11], v[112:113] op_sel_hi:[1,0,1]
	v_and_b32_e32 v112, 0xffff0000, v104
	v_lshlrev_b32_e32 v113, 16, v104
	v_and_b32_e32 v116, 0xffff0000, v108
	v_lshlrev_b32_e32 v117, 16, v108
	v_and_b32_e32 v104, 0xffff0000, v105
	v_lshlrev_b32_e32 v105, 16, v105
	v_and_b32_e32 v108, 0xffff0000, v109
	v_lshlrev_b32_e32 v109, 16, v109
	v_pk_fma_f32 v[112:113], v[116:117], s[10:11], v[112:113] op_sel_hi:[1,0,1]
	v_pk_fma_f32 v[116:117], v[108:109], s[10:11], v[104:105] op_sel_hi:[1,0,1]
	v_and_b32_e32 v104, 0xffff0000, v106
	v_lshlrev_b32_e32 v105, 16, v106
	v_and_b32_e32 v108, 0xffff0000, v110
	v_lshlrev_b32_e32 v109, 16, v110
	v_pk_fma_f32 v[118:119], v[108:109], s[10:11], v[104:105] op_sel_hi:[1,0,1]
	v_and_b32_e32 v104, 0xffff0000, v107
	v_lshlrev_b32_e32 v105, 16, v107
	v_and_b32_e32 v106, 0xffff0000, v111
	v_lshlrev_b32_e32 v107, 16, v111
	v_pk_fma_f32 v[140:141], v[106:107], s[10:11], v[104:105] op_sel_hi:[1,0,1]
	v_and_b32_e32 v104, 0xffff0000, v96
	v_lshlrev_b32_e32 v105, 16, v96
	v_and_b32_e32 v106, 0xffff0000, v100
	v_lshlrev_b32_e32 v107, 16, v100
	v_and_b32_e32 v96, 0xffff0000, v97
	v_lshlrev_b32_e32 v97, 16, v97
	v_and_b32_e32 v100, 0xffff0000, v101
	v_lshlrev_b32_e32 v101, 16, v101
	v_pk_fma_f32 v[146:147], v[100:101], s[10:11], v[96:97] op_sel_hi:[1,0,1]
	v_and_b32_e32 v96, 0xffff0000, v98
	v_lshlrev_b32_e32 v97, 16, v98
	v_and_b32_e32 v100, 0xffff0000, v102
	v_lshlrev_b32_e32 v101, 16, v102
	v_pk_fma_f32 v[148:149], v[100:101], s[10:11], v[96:97] op_sel_hi:[1,0,1]
	v_and_b32_e32 v96, 0xffff0000, v99
	v_lshlrev_b32_e32 v97, 16, v99
	v_and_b32_e32 v98, 0xffff0000, v103
	v_lshlrev_b32_e32 v99, 16, v103
	v_pk_fma_f32 v[144:145], v[106:107], s[10:11], v[104:105] op_sel_hi:[1,0,1]
	v_pk_fma_f32 v[150:151], v[98:99], s[10:11], v[96:97] op_sel_hi:[1,0,1]
	v_cmp_lt_i32_e32 vcc, s13, v152
	s_and_saveexec_b64 s[2:3], vcc
	s_cbranch_execz .LBB0_2388
; __device__ __forceinline__ void ph_ln(const Args& a, int L, int which, bool final_, bool split, bool wr_x, bool res_inputs, int nblk, int b) {
;     ...
;         if (split && r >= MP) {
; #pragma unroll
;             for (int p = 0; p < 3; ++p) { const u32x4* pr = (const u32x4*)(P + ((size_t)p * MS + (r - MP)) * D) + lane;
; #pragma unroll
;                 for (int j = 0; j < 4; ++j) { const u32x4 w = pr[64 * j];
; #pragma unroll
;                     for (int e = 0; e < 4; ++e) { v[j][2 * e] += lo(w[e]); v[j][2 * e + 1] += hi(w[e]); } } } }
	v_add_u32_e32 v128, 0xffffe000, v152
	v_lshlrev_b64 v[96:97], 12, v[128:129]
	v_lshl_add_u64 v[96:97], v[130:131], 0, v[96:97]
	v_add_co_u32_e32 v98, vcc, s14, v96
	global_load_dwordx4 v[156:159], v[96:97], off nt
	global_load_dwordx4 v[104:107], v[96:97], off offset:1024 nt
	v_addc_co_u32_e32 v99, vcc, 0, v97, vcc
	global_load_dwordx4 v[160:163], v[98:99], off nt
	global_load_dwordx4 v[108:111], v[98:99], off offset:1024 nt
	v_add_co_u32_e32 v184, vcc, s15, v96
	s_waitcnt vmcnt(3)
	v_and_b32_e32 v188, 0xffff0000, v156
	v_addc_co_u32_e32 v185, vcc, 0, v97, vcc
	global_load_dwordx4 v[164:167], v[184:185], off nt
	global_load_dwordx4 v[168:171], v[184:185], off offset:1024 nt
	global_load_dwordx4 v[172:175], v[96:97], off offset:2048 nt
	global_load_dwordx4 v[176:179], v[98:99], off offset:2048 nt
	global_load_dwordx4 v[100:103], v[96:97], off offset:3072 nt
	s_nop 0
	global_load_dwordx4 v[96:99], v[98:99], off offset:3072 nt
	s_nop 0
	global_load_dwordx4 v[180:183], v[184:185], off offset:2048 nt
	s_nop 0
	global_load_dwordx4 v[184:187], v[184:185], off offset:3072 nt
	v_lshlrev_b32_e32 v189, 16, v156
	v_and_b32_e32 v156, 0xffff0000, v157
	v_lshlrev_b32_e32 v157, 16, v157
	v_and_b32_e32 v190, 0xffff0000, v158
	v_lshlrev_b32_e32 v191, 16, v158
	v_and_b32_e32 v158, 0xffff0000, v159
	v_lshlrev_b32_e32 v159, 16, v159
	s_waitcnt vmcnt(10)
	v_and_b32_e32 v192, 0xffff0000, v104
	v_lshlrev_b32_e32 v193, 16, v104
	v_and_b32_e32 v104, 0xffff0000, v105
	v_lshlrev_b32_e32 v105, 16, v105
	v_and_b32_e32 v194, 0xffff0000, v106
	v_lshlrev_b32_e32 v195, 16, v106
	v_pk_add_f32 v[120:121], v[120:121], v[156:157]
	v_pk_add_f32 v[126:127], v[126:127], v[158:159]
	v_pk_add_f32 v[104:105], v[138:139], v[104:105]
	v_pk_add_f32 v[138:139], v[142:143], v[194:195]
	s_waitcnt vmcnt(9)
	v_and_b32_e32 v142, 0xffff0000, v160
	v_lshlrev_b32_e32 v143, 16, v160
	v_and_b32_e32 v156, 0xffff0000, v161
	v_lshlrev_b32_e32 v157, 16, v161
	v_and_b32_e32 v158, 0xffff0000, v162
	v_lshlrev_b32_e32 v159, 16, v162
	v_and_b32_e32 v160, 0xffff0000, v163
	v_lshlrev_b32_e32 v161, 16, v163
	s_waitcnt vmcnt(8)
	v_and_b32_e32 v162, 0xffff0000, v108
	v_lshlrev_b32_e32 v163, 16, v108
	v_and_b32_e32 v108, 0xffff0000, v109
	v_lshlrev_b32_e32 v109, 16, v109
	v_pk_add_f32 v[136:137], v[136:137], v[188:189]
	v_and_b32_e32 v188, 0xffff0000, v110
	v_lshlrev_b32_e32 v189, 16, v110
	v_pk_add_f32 v[104:105], v[104:105], v[108:109]
	v_pk_add_f32 v[136:137], v[136:137], v[142:143]
	v_pk_add_f32 v[120:121], v[120:121], v[156:157]
	v_and_b32_e32 v106, 0xffff0000, v111
	v_pk_add_f32 v[124:125], v[124:125], v[190:191]
	v_pk_add_f32 v[122:123], v[122:123], v[192:193]
	v_pk_add_f32 v[124:125], v[124:125], v[158:159]
	v_pk_add_f32 v[126:127], v[126:127], v[160:161]
	v_pk_add_f32 v[122:123], v[122:123], v[162:163]
	s_waitcnt vmcnt(7)
	v_and_b32_e32 v142, 0xffff0000, v164
	s_waitcnt vmcnt(6)
	v_and_b32_e32 v108, 0xffff0000, v169
	v_lshlrev_b32_e32 v109, 16, v169
	v_lshlrev_b32_e32 v143, 16, v164
	v_and_b32_e32 v156, 0xffff0000, v165
	v_lshlrev_b32_e32 v157, 16, v165
	v_pk_add_f32 v[164:165], v[138:139], v[188:189]
	v_pk_add_f32 v[138:139], v[104:105], v[108:109]
	v_and_b32_e32 v104, 0xffff0000, v107
	v_lshlrev_b32_e32 v105, 16, v107
	v_pk_add_f32 v[104:105], v[114:115], v[104:105]
	v_lshlrev_b32_e32 v107, 16, v111
	v_pk_add_f32 v[104:105], v[104:105], v[106:107]
	v_and_b32_e32 v106, 0xffff0000, v171
	v_lshlrev_b32_e32 v107, 16, v171
	v_pk_add_f32 v[114:115], v[104:105], v[106:107]
	s_waitcnt vmcnt(5)
	v_and_b32_e32 v104, 0xffff0000, v172
	v_lshlrev_b32_e32 v105, 16, v172
	v_pk_add_f32 v[104:105], v[112:113], v[104:105]
	s_waitcnt vmcnt(4)
	v_and_b32_e32 v106, 0xffff0000, v176
	v_lshlrev_b32_e32 v107, 16, v176
	v_pk_add_f32 v[104:105], v[104:105], v[106:107]
	s_waitcnt vmcnt(1)
	v_and_b32_e32 v106, 0xffff0000, v180
	v_lshlrev_b32_e32 v107, 16, v180
	v_pk_add_f32 v[112:113], v[104:105], v[106:107]
	v_and_b32_e32 v104, 0xffff0000, v173
	v_lshlrev_b32_e32 v105, 16, v173
	v_pk_add_f32 v[104:105], v[116:117], v[104:105]
	v_and_b32_e32 v106, 0xffff0000, v177
	v_lshlrev_b32_e32 v107, 16, v177
	v_pk_add_f32 v[104:105], v[104:105], v[106:107]
	v_and_b32_e32 v106, 0xffff0000, v181
	v_lshlrev_b32_e32 v107, 16, v181
	v_pk_add_f32 v[116:117], v[104:105], v[106:107]
	v_and_b32_e32 v104, 0xffff0000, v174
	v_lshlrev_b32_e32 v105, 16, v174
	v_pk_add_f32 v[104:105], v[118:119], v[104:105]
	v_and_b32_e32 v106, 0xffff0000, v178
	v_lshlrev_b32_e32 v107, 16, v178
	v_pk_add_f32 v[104:105], v[104:105], v[106:107]
	v_and_b32_e32 v106, 0xffff0000, v182
	v_lshlrev_b32_e32 v107, 16, v182
	v_pk_add_f32 v[118:119], v[104:105], v[106:107]
	v_and_b32_e32 v104, 0xffff0000, v175
	v_lshlrev_b32_e32 v105, 16, v175
	v_pk_add_f32 v[104:105], v[140:141], v[104:105]
	v_and_b32_e32 v106, 0xffff0000, v179
	v_lshlrev_b32_e32 v107, 16, v179
	v_pk_add_f32 v[104:105], v[104:105], v[106:107]
	v_and_b32_e32 v106, 0xffff0000, v183
	v_lshlrev_b32_e32 v107, 16, v183
	v_pk_add_f32 v[140:141], v[104:105], v[106:107]
	v_and_b32_e32 v104, 0xffff0000, v100
	v_lshlrev_b32_e32 v105, 16, v100
	v_and_b32_e32 v100, 0xffff0000, v101
	v_lshlrev_b32_e32 v101, 16, v101
	v_and_b32_e32 v106, 0xffff0000, v96
	v_lshlrev_b32_e32 v107, 16, v96
	v_pk_add_f32 v[100:101], v[146:147], v[100:101]
	v_and_b32_e32 v96, 0xffff0000, v97
	v_lshlrev_b32_e32 v97, 16, v97
	v_pk_add_f32 v[96:97], v[100:101], v[96:97]
	s_waitcnt vmcnt(0)
	v_and_b32_e32 v100, 0xffff0000, v185
	v_lshlrev_b32_e32 v101, 16, v185
	v_pk_add_f32 v[146:147], v[96:97], v[100:101]
	v_and_b32_e32 v96, 0xffff0000, v102
	v_lshlrev_b32_e32 v97, 16, v102
	v_pk_add_f32 v[96:97], v[148:149], v[96:97]
	v_and_b32_e32 v100, 0xffff0000, v98
	v_lshlrev_b32_e32 v101, 16, v98
	v_pk_add_f32 v[96:97], v[96:97], v[100:101]
	v_and_b32_e32 v100, 0xffff0000, v186
	v_lshlrev_b32_e32 v101, 16, v186
	v_pk_add_f32 v[148:149], v[96:97], v[100:101]
	v_and_b32_e32 v96, 0xffff0000, v103
	v_lshlrev_b32_e32 v97, 16, v103
	v_pk_add_f32 v[104:105], v[144:145], v[104:105]
	v_pk_add_f32 v[96:97], v[150:151], v[96:97]
	v_and_b32_e32 v98, 0xffff0000, v99
	v_lshlrev_b32_e32 v99, 16, v99
	v_and_b32_e32 v158, 0xffff0000, v166
	v_lshlrev_b32_e32 v159, 16, v166
	v_and_b32_e32 v160, 0xffff0000, v167
	v_lshlrev_b32_e32 v161, 16, v167
	v_and_b32_e32 v162, 0xffff0000, v168
	v_lshlrev_b32_e32 v163, 16, v168
	v_and_b32_e32 v166, 0xffff0000, v170
	v_lshlrev_b32_e32 v167, 16, v170
	v_pk_add_f32 v[104:105], v[104:105], v[106:107]
	v_and_b32_e32 v106, 0xffff0000, v184
	v_lshlrev_b32_e32 v107, 16, v184
	v_pk_add_f32 v[96:97], v[96:97], v[98:99]
	v_and_b32_e32 v98, 0xffff0000, v187
	v_lshlrev_b32_e32 v99, 16, v187
	v_pk_add_f32 v[136:137], v[136:137], v[142:143]
	v_pk_add_f32 v[120:121], v[120:121], v[156:157]
	v_pk_add_f32 v[124:125], v[124:125], v[158:159]
	v_pk_add_f32 v[126:127], v[126:127], v[160:161]
	v_pk_add_f32 v[122:123], v[122:123], v[162:163]
	v_pk_add_f32 v[142:143], v[164:165], v[166:167]
	v_pk_add_f32 v[144:145], v[104:105], v[106:107]
	v_pk_add_f32 v[150:151], v[96:97], v[98:99]
	s_branch .LBB0_2388
